# speedup vs baseline: 1.0396x; 1.0019x over previous
; __device__ __forceinline__ float bf2f(unsigned short h) { return __uint_as_float(((unsigned)h) << 16); }
; template <int T> __device__ __forceinline__ float conv_tok(const float (&w)[31], const float (&vin)[62], float bias) {
;     ...
;   for (int k = 0; k < 31; ++k) s = fmaf(w[k], vin[T + k], s);
; __global__ void __launch_bounds__(512) fwd_megakernel(Params p) {
;     ...
;       for (int ci_ = blockIdx.x; ci_ < nci * CONV_REP; ci_ += G) {
;         const int ci = CONV_REP > 1 ? ci_ % nci : ci_;
;         int b = ci >> 6, s0 = (ci & 63) * 32;
;         const unsigned short* ub = (const unsigned short*)p_u0 + ((long)b * LTOK + s0 + 1) * CONVC + c;
;         float vin[62];
;         #pragma unroll
;         for (int i2 = 0; i2 < 62; ++i2) {
;           const int i2c = min(i2, LTOK - 2 - s0);
;           float v = bf2f(ub[i2c * CONVC]);
;           vin[i2] = (s0 + 1 + i2 >= LTOK) ? 0.f : v;
;         }
;         float a[32];
;         conv_all(a, w, vin, cbias, std::make_integer_sequence<int, 32>{});
.LBB0_544:
	s_ashr_i32 s2, s40, 6
	s_and_b32 s41, s29, 0x7e0
	s_ashr_i32 s3, s2, 31
	s_mul_i32 s0, s2, 0x810
	s_mul_hi_i32 s1, s2, 0x810
	s_add_u32 s0, s0, s41
	s_addc_u32 s1, s1, 0
	s_lshl_b64 s[0:1], s[0:1], 10
	v_lshl_add_u64 v[26:27], v[18:19], 0, s[0:1]
	v_add_co_u32_e32 v28, vcc, s16, v26
	s_sub_i32 s42, 0x80e, s41
	s_nop 0
	v_addc_co_u32_e32 v29, vcc, 0, v27, vcc
	v_add_co_u32_e32 v74, vcc, s17, v26
	s_min_u32 s4, s42, 47
	s_nop 0
	v_addc_co_u32_e32 v75, vcc, 0, v27, vcc
	v_add_co_u32_e32 v76, vcc, s18, v26
	s_lshl_b32 s10, s4, 10
	s_nop 0
	v_addc_co_u32_e32 v77, vcc, 0, v27, vcc
	v_add_co_u32_e32 v78, vcc, s19, v26
	s_cmpk_lg_i32 s41, 0x7e0
	s_nop 0
	v_addc_co_u32_e32 v79, vcc, 0, v27, vcc
	s_waitcnt vmcnt(62)
	v_add_co_u32_e32 v80, vcc, s20, v26
	v_lshl_add_u64 v[94:95], v[26:27], 0, s[10:11]
	s_nop 0
	v_addc_co_u32_e32 v81, vcc, 0, v27, vcc
	v_add_co_u32_e32 v82, vcc, s21, v26
	s_nop 1
	v_addc_co_u32_e32 v83, vcc, 0, v27, vcc
	v_add_co_u32_e32 v84, vcc, s22, v26
	s_nop 1
	v_addc_co_u32_e32 v85, vcc, 0, v27, vcc
	v_add_co_u32_e32 v86, vcc, s23, v26
	s_nop 1
	v_addc_co_u32_e32 v87, vcc, 0, v27, vcc
	v_add_co_u32_e32 v88, vcc, s24, v26
	s_nop 1
	v_addc_co_u32_e32 v89, vcc, 0, v27, vcc
	v_add_co_u32_e32 v90, vcc, s25, v26
	s_nop 1
	v_addc_co_u32_e32 v91, vcc, 0, v27, vcc
	v_add_co_u32_e32 v92, vcc, s28, v26
	s_nop 1
	v_addc_co_u32_e32 v93, vcc, 0, v27, vcc
	global_load_ushort v96, v[26:27], off
	global_load_ushort v97, v[26:27], off offset:1024
	global_load_ushort v98, v[26:27], off offset:2048
	global_load_ushort v99, v[26:27], off offset:3072
	global_load_ushort v101, v[28:29], off offset:1024
	global_load_ushort v103, v[28:29], off offset:2048
	global_load_ushort v104, v[28:29], off offset:3072
	global_load_ushort v105, v[74:75], off
	global_load_ushort v106, v[74:75], off offset:1024
	global_load_ushort v107, v[74:75], off offset:2048
	global_load_ushort v108, v[74:75], off offset:3072
	global_load_ushort v109, v[78:79], off offset:-4096
	global_load_ushort v110, v[76:77], off offset:1024
	global_load_ushort v111, v[76:77], off offset:2048
	s_nop 0
	global_load_ushort v76, v[76:77], off offset:3072
	s_nop 0
	global_load_ushort v77, v[78:79], off
	global_load_ushort v112, v[78:79], off offset:1024
	global_load_ushort v113, v[78:79], off offset:2048
	s_nop 0
	global_load_ushort v78, v[78:79], off offset:3072
	s_nop 0
	global_load_ushort v79, v[82:83], off offset:-4096
	global_load_ushort v114, v[80:81], off offset:1024
	global_load_ushort v115, v[80:81], off offset:2048
	s_nop 0
	global_load_ushort v80, v[80:81], off offset:3072
	s_nop 0
	global_load_ushort v81, v[82:83], off
	global_load_ushort v116, v[82:83], off offset:1024
	global_load_ushort v117, v[82:83], off offset:2048
	global_load_ushort v118, v[82:83], off offset:3072
	global_load_ushort v119, v[86:87], off offset:-4096
	global_load_ushort v120, v[84:85], off offset:1024
	global_load_ushort v121, v[84:85], off offset:2048
	global_load_ushort v122, v[84:85], off offset:3072
	global_load_ushort v123, v[86:87], off
	global_load_ushort v124, v[86:87], off offset:1024
	global_load_ushort v127, v[86:87], off offset:2048
	global_load_ushort v129, v[86:87], off offset:3072
	global_load_ushort v130, v[90:91], off offset:-4096
	global_load_ushort v131, v[88:89], off offset:1024
	global_load_ushort v132, v[88:89], off offset:2048
	global_load_ushort v133, v[88:89], off offset:3072
	global_load_ushort v134, v[90:91], off
	global_load_ushort v135, v[90:91], off offset:1024
	global_load_ushort v136, v[90:91], off offset:2048
	global_load_ushort v137, v[90:91], off offset:3072
	global_load_ushort v138, v[92:93], off
	global_load_ushort v139, v[92:93], off offset:1024
	global_load_ushort v140, v[92:93], off offset:2048
	global_load_ushort v141, v[94:95], off
	global_load_ushort v100, v[74:75], off offset:-4096
	s_cselect_b64 vcc, -1, 0
	s_min_u32 s0, s42, 48
	s_lshl_b32 s10, s0, 10
	v_lshl_add_u64 v[28:29], v[26:27], 0, s[10:11]
	global_load_ushort v125, v[28:29], off
	s_cmpk_lt_u32 s41, 0x7df
	s_waitcnt vmcnt(48)
	v_lshlrev_b32_e32 v142, 16, v96
	s_waitcnt vmcnt(47)
	v_lshlrev_b32_e32 v143, 16, v97
	s_waitcnt vmcnt(46)
	v_lshlrev_b32_e32 v128, 16, v98
	s_waitcnt vmcnt(45)
	v_lshlrev_b32_e32 v126, 16, v99
	s_waitcnt vmcnt(44)
	v_lshlrev_b32_e32 v102, 16, v101
	s_waitcnt vmcnt(43)
	v_lshlrev_b32_e32 v101, 16, v103
	v_fma_f32 v103, v59, v142, v61
	s_waitcnt vmcnt(42)
	v_lshlrev_b32_e32 v99, 16, v104
	v_fma_f32 v104, v59, v143, v61
	v_fmac_f32_e32 v103, v60, v143
	s_waitcnt vmcnt(41)
	v_lshlrev_b32_e32 v98, 16, v105
	v_fma_f32 v105, v59, v128, v61
	v_fmac_f32_e32 v104, v60, v128
	v_fmac_f32_e32 v103, v30, v128
	v_fmac_f32_e32 v105, v60, v126
	s_waitcnt vmcnt(33)
	v_lshlrev_b32_e32 v90, 16, v77
	v_fmac_f32_e32 v104, v30, v126
	v_fmac_f32_e32 v103, v31, v126
	s_waitcnt vmcnt(30)
	v_lshlrev_b32_e32 v87, 16, v78
	s_waitcnt vmcnt(29)
	v_lshlrev_b32_e32 v86, 16, v79
	v_lshlrev_b32_e32 v91, 16, v76
	v_lshlrev_b32_e32 v97, 16, v106
	s_waitcnt vmcnt(28)
	v_lshlrev_b32_e32 v85, 16, v114
	s_waitcnt vmcnt(25)
	v_lshlrev_b32_e32 v82, 16, v81
	s_waitcnt vmcnt(24)
	v_lshlrev_b32_e32 v81, 16, v116
	v_lshlrev_b32_e32 v83, 16, v80
	s_waitcnt vmcnt(22)
	v_lshlrev_b32_e32 v79, 16, v118
	s_waitcnt vmcnt(21)
	v_lshlrev_b32_e32 v78, 16, v119
	s_waitcnt vmcnt(20)
	v_lshlrev_b32_e32 v77, 16, v120
	v_fma_f32 v118, v59, v126, v61
	s_waitcnt vmcnt(19)
	v_lshlrev_b32_e32 v76, 16, v121
	v_fma_f32 v121, v59, v101, v61
	s_waitcnt vmcnt(18)
	v_lshlrev_b32_e32 v75, 16, v122
	v_fma_f32 v122, v59, v99, v61
	v_fmac_f32_e32 v121, v60, v99
	v_lshlrev_b32_e32 v80, 16, v117
	s_waitcnt vmcnt(17)
; __device__ __forceinline__ float bf2f(unsigned short h) { return __uint_as_float(((unsigned)h) << 16); }
; template <int T> __device__ __forceinline__ float conv_tok(const float (&w)[31], const float (&vin)[62], float bias) {
;   float s = bias;
;   #pragma unroll
;   for (int k = 0; k < 31; ++k) s = fmaf(w[k], vin[T + k], s);
;   return s;
; __global__ void __launch_bounds__(512) fwd_megakernel(Params p) {
;     ...
;         #pragma unroll
;         for (int i2 = 0; i2 < 62; ++i2) {
;           const int i2c = min(i2, LTOK - 2 - s0);
;           float v = bf2f(ub[i2c * CONVC]);
;           vin[i2] = (s0 + 1 + i2 >= LTOK) ? 0.f : v;
;         }
;         float a[32];
;         conv_all(a, w, vin, cbias, std::make_integer_sequence<int, 32>{});
	v_lshlrev_b32_e32 v74, 16, v123
	v_fma_f32 v123, v59, v98, v61
	v_fmac_f32_e32 v122, v60, v98
	v_fmac_f32_e32 v121, v30, v98
	v_lshlrev_b32_e32 v96, 16, v107
	v_lshlrev_b32_e32 v84, 16, v115
	v_fmac_f32_e32 v123, v60, v97
	v_fmac_f32_e32 v122, v30, v97
	s_waitcnt vmcnt(4)
	v_lshlrev_b32_e32 v116, 16, v139
	v_fma_f32 v139, v59, v87, v61
	s_waitcnt vmcnt(2)
	v_lshlrev_b32_e32 v119, 16, v141
	v_cndmask_b32_e32 v120, 0, v119, vcc
	s_cselect_b64 vcc, -1, 0
	s_min_u32 s0, s42, 49
	s_lshl_b32 s10, s0, 10
	v_lshl_add_u64 v[152:153], v[26:27], 0, s[10:11]
	s_cmpk_lt_u32 s41, 0x7de
	global_load_ushort v126, v[152:153], off
	s_waitcnt vmcnt(1)
	v_lshlrev_b32_e32 v125, 16, v125
	v_cndmask_b32_e32 v125, 0, v125, vcc
	s_cselect_b64 vcc, -1, 0
	s_min_u32 s0, s42, 50
	s_lshl_b32 s10, s0, 10
	s_cmpk_lt_u32 s41, 0x7dd
	s_cselect_b64 s[4:5], -1, 0
	s_min_u32 s0, s42, 51
	v_lshl_add_u64 v[152:153], v[26:27], 0, s[10:11]
	s_lshl_b32 s10, s0, 10
	s_cmpk_lt_u32 s41, 0x7dc
	s_cselect_b64 s[6:7], -1, 0
	s_min_u32 s0, s42, 52
	global_load_ushort v128, v[152:153], off
	v_lshl_add_u64 v[152:153], v[26:27], 0, s[10:11]
	s_lshl_b32 s10, s0, 10
	s_cmpk_lt_u32 s41, 0x7db
	s_cselect_b64 s[8:9], -1, 0
	s_min_u32 s0, s42, 53
	v_lshl_add_u64 v[154:155], v[26:27], 0, s[10:11]
	s_lshl_b32 s10, s0, 10
	global_load_ushort v152, v[152:153], off
	s_cmpk_lt_u32 s41, 0x7da
	global_load_ushort v153, v[154:155], off
	v_lshl_add_u64 v[154:155], v[26:27], 0, s[10:11]
	s_cselect_b64 s[0:1], -1, 0
	s_min_u32 s10, s42, 54
	s_lshl_b32 s10, s10, 10
	s_cmpk_lt_u32 s41, 0x7d9
	global_load_ushort v156, v[154:155], off
	v_lshl_add_u64 v[154:155], v[26:27], 0, s[10:11]
	s_cselect_b64 s[12:13], -1, 0
	s_min_u32 s10, s42, 55
	s_lshl_b32 s10, s10, 10
	global_load_ushort v157, v[154:155], off
	s_cmpk_lt_u32 s41, 0x7d8
	v_lshl_add_u64 v[154:155], v[26:27], 0, s[10:11]
	s_cselect_b64 s[14:15], -1, 0
	s_min_u32 s10, s42, 56
	global_load_ushort v158, v[154:155], off
	s_lshl_b32 s10, s10, 10
	v_lshl_add_u64 v[154:155], v[26:27], 0, s[10:11]
	global_load_ushort v154, v[154:155], off
	v_fma_f32 v119, v59, v102, v61
	v_fmac_f32_e32 v119, v60, v101
	v_fmac_f32_e32 v119, v30, v99
	v_lshlrev_b32_e32 v117, 16, v140
	v_fma_f32 v140, v59, v86, v61
	v_fmac_f32_e32 v139, v60, v86
	v_fmac_f32_e32 v119, v31, v98
	v_lshlrev_b32_e32 v28, 16, v124
	v_fma_f32 v124, v59, v97, v61
	v_fma_f32 v141, v59, v85, v61
	v_fmac_f32_e32 v140, v60, v85
	v_fmac_f32_e32 v139, v30, v85
	v_fmac_f32_e32 v121, v31, v97
	v_fmac_f32_e32 v119, v32, v97
	v_lshlrev_b32_e32 v95, 16, v108
	v_lshlrev_b32_e32 v29, 16, v127
	v_fma_f32 v127, v59, v96, v61
	v_fma_f32 v142, v59, v84, v61
	v_fmac_f32_e32 v124, v60, v96
	v_fmac_f32_e32 v141, v60, v84
	v_fmac_f32_e32 v123, v30, v96
	v_fmac_f32_e32 v140, v30, v84
	v_fmac_f32_e32 v122, v31, v96
	v_fmac_f32_e32 v139, v31, v84
	v_fmac_f32_e32 v121, v32, v96
	v_fmac_f32_e32 v119, v33, v96
	v_lshlrev_b32_e32 v94, 16, v109
	v_lshlrev_b32_e32 v106, 16, v129
	v_fma_f32 v129, v59, v95, v61
	v_fma_f32 v146, v59, v83, v61
	v_fmac_f32_e32 v127, v60, v95
	v_fmac_f32_e32 v142, v60, v83
	v_fmac_f32_e32 v124, v30, v95
	v_fmac_f32_e32 v141, v30, v83
	v_fmac_f32_e32 v123, v31, v95
	v_fmac_f32_e32 v140, v31, v83
	v_fmac_f32_e32 v122, v32, v95
	v_fmac_f32_e32 v139, v32, v83
	v_fmac_f32_e32 v121, v33, v95
	v_fmac_f32_e32 v119, v34, v95
	v_lshlrev_b32_e32 v93, 16, v110
	v_lshlrev_b32_e32 v107, 16, v130
	v_fma_f32 v130, v59, v94, v61
	v_fma_f32 v148, v59, v82, v61
	v_fmac_f32_e32 v129, v60, v94
	v_fmac_f32_e32 v146, v60, v82
	v_fmac_f32_e32 v127, v30, v94
	v_fmac_f32_e32 v142, v30, v82
	v_fmac_f32_e32 v124, v31, v94
	v_fmac_f32_e32 v141, v31, v82
	v_fmac_f32_e32 v123, v32, v94
	v_fmac_f32_e32 v140, v32, v82
	v_fmac_f32_e32 v122, v33, v94
	v_fmac_f32_e32 v139, v33, v82
	v_fmac_f32_e32 v121, v34, v94
	v_fmac_f32_e32 v119, v35, v94
	v_lshlrev_b32_e32 v92, 16, v111
	v_lshlrev_b32_e32 v108, 16, v131
	v_fma_f32 v131, v59, v93, v61
	v_fma_f32 v150, v59, v81, v61
	v_fmac_f32_e32 v130, v60, v93
	v_fmac_f32_e32 v148, v60, v81
	v_fmac_f32_e32 v129, v30, v93
	v_fmac_f32_e32 v146, v30, v81
	v_fmac_f32_e32 v127, v31, v93
	v_fmac_f32_e32 v142, v31, v81
	v_fmac_f32_e32 v124, v32, v93
	v_fmac_f32_e32 v141, v32, v81
	v_fmac_f32_e32 v123, v33, v93
	v_fmac_f32_e32 v140, v33, v81
	v_fmac_f32_e32 v122, v34, v93
	v_fmac_f32_e32 v139, v34, v81
	v_fmac_f32_e32 v121, v35, v93
	v_fmac_f32_e32 v119, v36, v93
	v_lshlrev_b32_e32 v109, 16, v132
	v_fma_f32 v132, v59, v92, v61
	v_fma_f32 v143, v59, v80, v61
	v_fmac_f32_e32 v131, v60, v92
	v_fmac_f32_e32 v150, v60, v80
	v_fmac_f32_e32 v130, v30, v92
	v_fmac_f32_e32 v148, v30, v80
	v_fmac_f32_e32 v129, v31, v92
	v_fmac_f32_e32 v146, v31, v80
	v_fmac_f32_e32 v127, v32, v92
	v_fmac_f32_e32 v142, v32, v80
	v_fmac_f32_e32 v124, v33, v92
	v_fmac_f32_e32 v141, v33, v80
	v_fmac_f32_e32 v123, v34, v92
	v_fmac_f32_e32 v140, v34, v80
	v_fmac_f32_e32 v122, v35, v92
	v_fmac_f32_e32 v139, v35, v80
	v_fmac_f32_e32 v121, v36, v92
	v_fmac_f32_e32 v119, v37, v92
	v_lshlrev_b32_e32 v110, 16, v133
	v_fma_f32 v133, v59, v91, v61
	v_fma_f32 v147, v59, v79, v61
	v_fmac_f32_e32 v132, v60, v91
	v_fmac_f32_e32 v143, v60, v79
	v_fmac_f32_e32 v131, v30, v91
	v_fmac_f32_e32 v150, v30, v79
	v_fmac_f32_e32 v130, v31, v91
	v_fmac_f32_e32 v148, v31, v79
	v_fmac_f32_e32 v129, v32, v91
	v_fmac_f32_e32 v146, v32, v79
	v_fmac_f32_e32 v127, v33, v91
	v_fmac_f32_e32 v142, v33, v79
	v_fmac_f32_e32 v124, v34, v91
	v_fmac_f32_e32 v141, v34, v79
	v_fmac_f32_e32 v123, v35, v91
	v_fmac_f32_e32 v140, v35, v79
	v_fmac_f32_e32 v122, v36, v91
	v_fmac_f32_e32 v139, v36, v79
	v_fmac_f32_e32 v121, v37, v91
	v_fmac_f32_e32 v119, v38, v91
	v_lshlrev_b32_e32 v89, 16, v112
; template <int T> __device__ __forceinline__ float conv_tok(const float (&w)[31], const float (&vin)[62], float bias) {
;   float s = bias;
;   #pragma unroll
;   for (int k = 0; k < 31; ++k) s = fmaf(w[k], vin[T + k], s);
;   return s;
; }
; template <int... Ts> __device__ __forceinline__ void conv_all(float (&a)[32], const float (&w)[31], const float (&vin)[62], float bias, std::integer_sequence<int, Ts...>) {
;   ((a[Ts] = conv_tok<Ts>(w, vin, bias)), ...);
	v_lshlrev_b32_e32 v112, 16, v135
	v_fma_f32 v135, v59, v90, v61
	v_fma_f32 v149, v59, v78, v61
	v_fmac_f32_e32 v133, v60, v90
	v_fmac_f32_e32 v147, v60, v78
	v_fmac_f32_e32 v132, v30, v90
	v_fmac_f32_e32 v143, v30, v78
	v_fmac_f32_e32 v131, v31, v90
	v_fmac_f32_e32 v150, v31, v78
	v_fmac_f32_e32 v130, v32, v90
	v_fmac_f32_e32 v148, v32, v78
	v_fmac_f32_e32 v129, v33, v90
	v_fmac_f32_e32 v146, v33, v78
	v_fmac_f32_e32 v127, v34, v90
	v_fmac_f32_e32 v142, v34, v78
	v_fmac_f32_e32 v124, v35, v90
	v_fmac_f32_e32 v141, v35, v78
	v_fmac_f32_e32 v123, v36, v90
	v_fmac_f32_e32 v140, v36, v78
	v_fmac_f32_e32 v122, v37, v90
	v_fmac_f32_e32 v139, v37, v78
	v_fmac_f32_e32 v121, v38, v90
	v_fmac_f32_e32 v119, v39, v90
	v_lshlrev_b32_e32 v88, 16, v113
	v_lshlrev_b32_e32 v114, 16, v137
	v_fma_f32 v137, v59, v89, v61
	v_fma_f32 v151, v59, v77, v61
	v_fmac_f32_e32 v135, v60, v89
	v_fmac_f32_e32 v149, v60, v77
	v_fmac_f32_e32 v133, v30, v89
	v_fmac_f32_e32 v147, v30, v77
	v_fmac_f32_e32 v132, v31, v89
	v_fmac_f32_e32 v143, v31, v77
	v_fmac_f32_e32 v131, v32, v89
	v_fmac_f32_e32 v150, v32, v77
	v_fmac_f32_e32 v130, v33, v89
	v_fmac_f32_e32 v148, v33, v77
	v_fmac_f32_e32 v129, v34, v89
	v_fmac_f32_e32 v146, v34, v77
	v_fmac_f32_e32 v127, v35, v89
	v_fmac_f32_e32 v142, v35, v77
	v_fmac_f32_e32 v124, v36, v89
	v_fmac_f32_e32 v141, v36, v77
	v_fmac_f32_e32 v123, v37, v89
	v_fmac_f32_e32 v140, v37, v77
	v_fmac_f32_e32 v122, v38, v89
	v_fmac_f32_e32 v139, v38, v77
	v_fmac_f32_e32 v121, v39, v89
	v_fmac_f32_e32 v119, v40, v89
	v_lshlrev_b32_e32 v111, 16, v134
	v_lshlrev_b32_e32 v115, 16, v138
	v_fma_f32 v138, v59, v88, v61
	v_fma_f32 v134, v59, v76, v61
	v_fmac_f32_e32 v137, v60, v88
	v_fmac_f32_e32 v151, v60, v76
	v_fmac_f32_e32 v135, v30, v88
	v_fmac_f32_e32 v149, v30, v76
	v_fmac_f32_e32 v133, v31, v88
	v_fmac_f32_e32 v147, v31, v76
	v_fmac_f32_e32 v132, v32, v88
	v_fmac_f32_e32 v143, v32, v76
	v_fmac_f32_e32 v131, v33, v88
	v_fmac_f32_e32 v150, v33, v76
	v_fmac_f32_e32 v130, v34, v88
	v_fmac_f32_e32 v148, v34, v76
	v_fmac_f32_e32 v129, v35, v88
	v_fmac_f32_e32 v146, v35, v76
	v_fmac_f32_e32 v127, v36, v88
	v_fmac_f32_e32 v142, v36, v76
	v_fmac_f32_e32 v124, v37, v88
	v_fmac_f32_e32 v141, v37, v76
	v_fmac_f32_e32 v123, v38, v88
	v_fmac_f32_e32 v140, v38, v76
	v_fmac_f32_e32 v122, v39, v88
	v_fmac_f32_e32 v139, v39, v76
	v_fmac_f32_e32 v121, v40, v88
	v_fmac_f32_e32 v119, v41, v88
	v_lshlrev_b32_e32 v113, 16, v136
	v_fma_f32 v136, v59, v75, v61
	v_fmac_f32_e32 v138, v60, v87
	v_fmac_f32_e32 v134, v60, v75
	v_fmac_f32_e32 v137, v30, v87
	v_fmac_f32_e32 v151, v30, v75
	v_fmac_f32_e32 v135, v31, v87
	v_fmac_f32_e32 v149, v31, v75
	v_fmac_f32_e32 v133, v32, v87
	v_fmac_f32_e32 v147, v32, v75
	v_fmac_f32_e32 v132, v33, v87
	v_fmac_f32_e32 v143, v33, v75
	v_fmac_f32_e32 v131, v34, v87
	v_fmac_f32_e32 v150, v34, v75
	v_fmac_f32_e32 v130, v35, v87
	v_fmac_f32_e32 v148, v35, v75
	v_fmac_f32_e32 v129, v36, v87
	v_fmac_f32_e32 v146, v36, v75
	v_fmac_f32_e32 v127, v37, v87
	v_fmac_f32_e32 v142, v37, v75
	v_fmac_f32_e32 v124, v38, v87
	v_fmac_f32_e32 v141, v38, v75
	v_fmac_f32_e32 v123, v39, v87
	v_fmac_f32_e32 v140, v39, v75
	v_fmac_f32_e32 v122, v40, v87
	v_fmac_f32_e32 v139, v40, v75
	v_fmac_f32_e32 v121, v41, v87
	v_fmac_f32_e32 v119, v42, v87
	v_fmac_f32_e32 v136, v60, v74
	v_fmac_f32_e32 v138, v30, v86
	v_fmac_f32_e32 v134, v30, v74
	v_fmac_f32_e32 v137, v31, v86
	v_fmac_f32_e32 v151, v31, v74
	v_fmac_f32_e32 v135, v32, v86
	v_fmac_f32_e32 v149, v32, v74
	v_fmac_f32_e32 v133, v33, v86
	v_fmac_f32_e32 v147, v33, v74
	v_fmac_f32_e32 v132, v34, v86
	v_fmac_f32_e32 v143, v34, v74
	v_fmac_f32_e32 v131, v35, v86
	v_fmac_f32_e32 v150, v35, v74
	v_fmac_f32_e32 v130, v36, v86
	v_fmac_f32_e32 v148, v36, v74
	v_fmac_f32_e32 v129, v37, v86
	v_fmac_f32_e32 v146, v37, v74
	v_fmac_f32_e32 v127, v38, v86
	v_fmac_f32_e32 v142, v38, v74
	v_fmac_f32_e32 v124, v39, v86
	v_fmac_f32_e32 v141, v39, v74
	v_fmac_f32_e32 v123, v40, v86
	v_fmac_f32_e32 v140, v40, v74
	v_fmac_f32_e32 v122, v41, v86
	v_fmac_f32_e32 v139, v41, v74
	v_fmac_f32_e32 v121, v42, v86
	v_fmac_f32_e32 v119, v43, v86
	v_fmac_f32_e32 v136, v30, v28
	v_fmac_f32_e32 v138, v31, v85
	v_fmac_f32_e32 v134, v31, v28
	v_fmac_f32_e32 v137, v32, v85
	v_fmac_f32_e32 v151, v32, v28
	v_fmac_f32_e32 v135, v33, v85
	v_fmac_f32_e32 v149, v33, v28
	v_fmac_f32_e32 v133, v34, v85
	v_fmac_f32_e32 v147, v34, v28
	v_fmac_f32_e32 v132, v35, v85
	v_fmac_f32_e32 v143, v35, v28
	v_fmac_f32_e32 v131, v36, v85
	v_fmac_f32_e32 v150, v36, v28
	v_fmac_f32_e32 v130, v37, v85
	v_fmac_f32_e32 v148, v37, v28
	v_fmac_f32_e32 v129, v38, v85
	v_fmac_f32_e32 v146, v38, v28
	v_fmac_f32_e32 v127, v39, v85
	v_fmac_f32_e32 v142, v39, v28
	v_fmac_f32_e32 v124, v40, v85
	v_fmac_f32_e32 v141, v40, v28
	v_fmac_f32_e32 v123, v41, v85
	v_fmac_f32_e32 v140, v41, v28
	v_fmac_f32_e32 v122, v42, v85
	v_fmac_f32_e32 v139, v42, v28
	v_fmac_f32_e32 v121, v43, v85
	v_fmac_f32_e32 v119, v44, v85
	v_fmac_f32_e32 v136, v31, v29
	v_fmac_f32_e32 v138, v32, v84
	v_fmac_f32_e32 v134, v32, v29
	v_fmac_f32_e32 v137, v33, v84
	v_fmac_f32_e32 v151, v33, v29
	v_fmac_f32_e32 v135, v34, v84
	v_fmac_f32_e32 v149, v34, v29
	v_fmac_f32_e32 v133, v35, v84
	v_fmac_f32_e32 v147, v35, v29
	v_fmac_f32_e32 v132, v36, v84
	v_fmac_f32_e32 v143, v36, v29
	v_fmac_f32_e32 v131, v37, v84
	v_fmac_f32_e32 v150, v37, v29
	v_fmac_f32_e32 v130, v38, v84
	v_fmac_f32_e32 v148, v38, v29
	v_fmac_f32_e32 v129, v39, v84
	v_fmac_f32_e32 v146, v39, v29
	v_fmac_f32_e32 v127, v40, v84
	v_fmac_f32_e32 v142, v40, v29
	v_fmac_f32_e32 v124, v41, v84
	v_fmac_f32_e32 v141, v41, v29
	v_fmac_f32_e32 v123, v42, v84
; template <int T> __device__ __forceinline__ float conv_tok(const float (&w)[31], const float (&vin)[62], float bias) {
;   float s = bias;
;   #pragma unroll
;   for (int k = 0; k < 31; ++k) s = fmaf(w[k], vin[T + k], s);
;   return s;
; }
; template <int... Ts> __device__ __forceinline__ void conv_all(float (&a)[32], const float (&w)[31], const float (&vin)[62], float bias, std::integer_sequence<int, Ts...>) {
;   ((a[Ts] = conv_tok<Ts>(w, vin, bias)), ...);
	v_fmac_f32_e32 v140, v42, v29
	v_fmac_f32_e32 v122, v43, v84
	v_fmac_f32_e32 v139, v43, v29
	v_fmac_f32_e32 v121, v44, v84
	v_fmac_f32_e32 v119, v45, v84
	v_fmac_f32_e32 v136, v32, v106
	v_fmac_f32_e32 v138, v33, v83
	v_fmac_f32_e32 v134, v33, v106
	v_fmac_f32_e32 v137, v34, v83
	v_fmac_f32_e32 v151, v34, v106
	v_fmac_f32_e32 v135, v35, v83
	v_fmac_f32_e32 v149, v35, v106
	v_fmac_f32_e32 v133, v36, v83
	v_fmac_f32_e32 v147, v36, v106
	v_fmac_f32_e32 v132, v37, v83
	v_fmac_f32_e32 v143, v37, v106
	v_fmac_f32_e32 v131, v38, v83
	v_fmac_f32_e32 v150, v38, v106
	v_fmac_f32_e32 v130, v39, v83
	v_fmac_f32_e32 v148, v39, v106
	v_fmac_f32_e32 v129, v40, v83
	v_fmac_f32_e32 v146, v40, v106
	v_fmac_f32_e32 v127, v41, v83
	v_fmac_f32_e32 v142, v41, v106
	v_fmac_f32_e32 v124, v42, v83
	v_fmac_f32_e32 v141, v42, v106
	v_fmac_f32_e32 v123, v43, v83
	v_fmac_f32_e32 v140, v43, v106
	v_fmac_f32_e32 v122, v44, v83
	v_fmac_f32_e32 v139, v44, v106
	v_fmac_f32_e32 v121, v45, v83
	v_fmac_f32_e32 v119, v46, v83
	v_fmac_f32_e32 v136, v33, v107
	v_fmac_f32_e32 v138, v34, v82
	v_fmac_f32_e32 v134, v34, v107
	v_fmac_f32_e32 v137, v35, v82
	v_fmac_f32_e32 v151, v35, v107
	v_fmac_f32_e32 v135, v36, v82
	v_fmac_f32_e32 v149, v36, v107
	v_fmac_f32_e32 v133, v37, v82
	v_fmac_f32_e32 v147, v37, v107
	v_fmac_f32_e32 v132, v38, v82
	v_fmac_f32_e32 v143, v38, v107
	v_fmac_f32_e32 v131, v39, v82
	v_fmac_f32_e32 v150, v39, v107
	v_fmac_f32_e32 v130, v40, v82
	v_fmac_f32_e32 v148, v40, v107
	v_fmac_f32_e32 v129, v41, v82
	v_fmac_f32_e32 v146, v41, v107
	v_fmac_f32_e32 v127, v42, v82
	v_fmac_f32_e32 v142, v42, v107
	v_fmac_f32_e32 v124, v43, v82
	v_fmac_f32_e32 v141, v43, v107
	v_fmac_f32_e32 v123, v44, v82
	v_fmac_f32_e32 v140, v44, v107
	v_fmac_f32_e32 v122, v45, v82
	v_fmac_f32_e32 v139, v45, v107
	v_fmac_f32_e32 v121, v46, v82
	v_fmac_f32_e32 v119, v47, v82
	v_fmac_f32_e32 v136, v34, v108
	v_fmac_f32_e32 v138, v35, v81
	v_fmac_f32_e32 v134, v35, v108
	v_fmac_f32_e32 v137, v36, v81
	v_fmac_f32_e32 v151, v36, v108
	v_fmac_f32_e32 v135, v37, v81
	v_fmac_f32_e32 v149, v37, v108
	v_fmac_f32_e32 v133, v38, v81
	v_fmac_f32_e32 v147, v38, v108
	v_fmac_f32_e32 v132, v39, v81
	v_fmac_f32_e32 v143, v39, v108
	v_fmac_f32_e32 v131, v40, v81
	v_fmac_f32_e32 v150, v40, v108
	v_fmac_f32_e32 v130, v41, v81
	v_fmac_f32_e32 v148, v41, v108
	v_fmac_f32_e32 v129, v42, v81
	v_fmac_f32_e32 v146, v42, v108
	v_fmac_f32_e32 v127, v43, v81
	v_fmac_f32_e32 v142, v43, v108
	v_fmac_f32_e32 v124, v44, v81
	v_fmac_f32_e32 v141, v44, v108
	v_fmac_f32_e32 v123, v45, v81
	v_fmac_f32_e32 v140, v45, v108
	v_fmac_f32_e32 v122, v46, v81
	v_fmac_f32_e32 v139, v46, v108
	v_fmac_f32_e32 v121, v47, v81
	v_fmac_f32_e32 v119, v48, v81
	v_fmac_f32_e32 v136, v35, v109
	v_fmac_f32_e32 v138, v36, v80
	v_fmac_f32_e32 v134, v36, v109
	v_fmac_f32_e32 v137, v37, v80
	v_fmac_f32_e32 v151, v37, v109
	v_fmac_f32_e32 v135, v38, v80
	v_fmac_f32_e32 v149, v38, v109
	v_fmac_f32_e32 v133, v39, v80
	v_fmac_f32_e32 v147, v39, v109
	v_fmac_f32_e32 v132, v40, v80
	v_fmac_f32_e32 v143, v40, v109
	v_fmac_f32_e32 v131, v41, v80
	v_fmac_f32_e32 v150, v41, v109
	v_fmac_f32_e32 v130, v42, v80
	v_fmac_f32_e32 v148, v42, v109
	v_fmac_f32_e32 v129, v43, v80
	v_fmac_f32_e32 v146, v43, v109
	v_fmac_f32_e32 v127, v44, v80
	v_fmac_f32_e32 v142, v44, v109
	v_fmac_f32_e32 v124, v45, v80
	v_fmac_f32_e32 v141, v45, v109
	v_fmac_f32_e32 v123, v46, v80
	v_fmac_f32_e32 v140, v46, v109
	v_fmac_f32_e32 v122, v47, v80
	v_fmac_f32_e32 v139, v47, v109
	v_fmac_f32_e32 v121, v48, v80
	v_fmac_f32_e32 v119, v49, v80
	v_fmac_f32_e32 v136, v36, v110
	v_fmac_f32_e32 v138, v37, v79
	v_fmac_f32_e32 v134, v37, v110
	v_fmac_f32_e32 v137, v38, v79
	v_fmac_f32_e32 v151, v38, v110
	v_fmac_f32_e32 v135, v39, v79
	v_fmac_f32_e32 v149, v39, v110
	v_fmac_f32_e32 v133, v40, v79
	v_fmac_f32_e32 v147, v40, v110
	v_fmac_f32_e32 v132, v41, v79
	v_fmac_f32_e32 v143, v41, v110
	v_fmac_f32_e32 v131, v42, v79
	v_fmac_f32_e32 v150, v42, v110
	v_fmac_f32_e32 v130, v43, v79
	v_fmac_f32_e32 v148, v43, v110
	v_fmac_f32_e32 v129, v44, v79
	v_fmac_f32_e32 v146, v44, v110
	v_fmac_f32_e32 v127, v45, v79
	v_fmac_f32_e32 v142, v45, v110
	v_fmac_f32_e32 v124, v46, v79
	v_fmac_f32_e32 v141, v46, v110
	v_fmac_f32_e32 v123, v47, v79
	v_fmac_f32_e32 v140, v47, v110
	v_fmac_f32_e32 v122, v48, v79
	v_fmac_f32_e32 v139, v48, v110
	v_fmac_f32_e32 v121, v49, v79
	v_fmac_f32_e32 v119, v50, v79
	v_fmac_f32_e32 v136, v37, v111
	v_fmac_f32_e32 v138, v38, v78
	v_fmac_f32_e32 v134, v38, v111
	v_fmac_f32_e32 v137, v39, v78
	v_fmac_f32_e32 v151, v39, v111
	v_fmac_f32_e32 v135, v40, v78
	v_fmac_f32_e32 v149, v40, v111
	v_fmac_f32_e32 v133, v41, v78
	v_fmac_f32_e32 v147, v41, v111
	v_fmac_f32_e32 v132, v42, v78
	v_fmac_f32_e32 v143, v42, v111
	v_fmac_f32_e32 v131, v43, v78
	v_fmac_f32_e32 v150, v43, v111
	v_fmac_f32_e32 v130, v44, v78
	v_fmac_f32_e32 v148, v44, v111
	v_fmac_f32_e32 v129, v45, v78
	v_fmac_f32_e32 v146, v45, v111
	v_fmac_f32_e32 v127, v46, v78
	v_fmac_f32_e32 v142, v46, v111
	v_fmac_f32_e32 v124, v47, v78
	v_fmac_f32_e32 v141, v47, v111
	v_fmac_f32_e32 v123, v48, v78
	v_fmac_f32_e32 v140, v48, v111
	v_fmac_f32_e32 v122, v49, v78
	v_fmac_f32_e32 v139, v49, v111
	v_fmac_f32_e32 v121, v50, v78
	v_fmac_f32_e32 v119, v51, v78
	v_fmac_f32_e32 v136, v38, v112
	v_fmac_f32_e32 v138, v39, v77
	v_fmac_f32_e32 v134, v39, v112
	v_fmac_f32_e32 v137, v40, v77
	v_fmac_f32_e32 v151, v40, v112
	v_fmac_f32_e32 v135, v41, v77
	v_fmac_f32_e32 v149, v41, v112
	v_fmac_f32_e32 v133, v42, v77
	v_fmac_f32_e32 v147, v42, v112
	v_fmac_f32_e32 v132, v43, v77
	v_fmac_f32_e32 v143, v43, v112
	v_fmac_f32_e32 v131, v44, v77
; template <int T> __device__ __forceinline__ float conv_tok(const float (&w)[31], const float (&vin)[62], float bias) {
;   float s = bias;
;   #pragma unroll
;   for (int k = 0; k < 31; ++k) s = fmaf(w[k], vin[T + k], s);
;   return s;
; }
; template <int... Ts> __device__ __forceinline__ void conv_all(float (&a)[32], const float (&w)[31], const float (&vin)[62], float bias, std::integer_sequence<int, Ts...>) {
;   ((a[Ts] = conv_tok<Ts>(w, vin, bias)), ...);
	v_fmac_f32_e32 v150, v44, v112
	v_fmac_f32_e32 v130, v45, v77
	v_fmac_f32_e32 v148, v45, v112
	v_fmac_f32_e32 v129, v46, v77
	v_fmac_f32_e32 v146, v46, v112
	v_fmac_f32_e32 v127, v47, v77
	v_fmac_f32_e32 v142, v47, v112
	v_fmac_f32_e32 v124, v48, v77
	v_fmac_f32_e32 v141, v48, v112
	v_fmac_f32_e32 v123, v49, v77
	v_fmac_f32_e32 v140, v49, v112
	v_fmac_f32_e32 v122, v50, v77
	v_fmac_f32_e32 v139, v50, v112
	v_fmac_f32_e32 v121, v51, v77
	v_fmac_f32_e32 v119, v52, v77
	v_fmac_f32_e32 v136, v39, v113
	v_fmac_f32_e32 v138, v40, v76
	v_fmac_f32_e32 v134, v40, v113
	v_fmac_f32_e32 v137, v41, v76
	v_fmac_f32_e32 v151, v41, v113
	v_fmac_f32_e32 v135, v42, v76
	v_fmac_f32_e32 v149, v42, v113
	v_fmac_f32_e32 v133, v43, v76
	v_fmac_f32_e32 v147, v43, v113
	v_fmac_f32_e32 v132, v44, v76
	v_fmac_f32_e32 v143, v44, v113
	v_fmac_f32_e32 v131, v45, v76
	v_fmac_f32_e32 v150, v45, v113
	v_fmac_f32_e32 v130, v46, v76
	v_fmac_f32_e32 v148, v46, v113
	v_fmac_f32_e32 v129, v47, v76
	v_fmac_f32_e32 v146, v47, v113
	v_fmac_f32_e32 v127, v48, v76
	v_fmac_f32_e32 v142, v48, v113
	v_fmac_f32_e32 v124, v49, v76
	v_fmac_f32_e32 v141, v49, v113
	v_fmac_f32_e32 v123, v50, v76
	v_fmac_f32_e32 v140, v50, v113
	v_fmac_f32_e32 v122, v51, v76
	v_fmac_f32_e32 v139, v51, v113
	v_fmac_f32_e32 v121, v52, v76
	v_fmac_f32_e32 v119, v53, v76
	v_fmac_f32_e32 v136, v40, v114
	v_fmac_f32_e32 v138, v41, v75
	v_fmac_f32_e32 v134, v41, v114
	v_fmac_f32_e32 v137, v42, v75
	v_fmac_f32_e32 v151, v42, v114
	v_fmac_f32_e32 v135, v43, v75
	v_fmac_f32_e32 v149, v43, v114
	v_fmac_f32_e32 v133, v44, v75
	v_fmac_f32_e32 v147, v44, v114
	v_fmac_f32_e32 v132, v45, v75
	v_fmac_f32_e32 v143, v45, v114
	v_fmac_f32_e32 v131, v46, v75
	v_fmac_f32_e32 v150, v46, v114
	v_fmac_f32_e32 v130, v47, v75
	v_fmac_f32_e32 v148, v47, v114
	v_fmac_f32_e32 v129, v48, v75
	v_fmac_f32_e32 v146, v48, v114
	v_fmac_f32_e32 v127, v49, v75
	v_fmac_f32_e32 v142, v49, v114
	v_fmac_f32_e32 v124, v50, v75
	v_fmac_f32_e32 v141, v50, v114
	v_fmac_f32_e32 v123, v51, v75
	v_fmac_f32_e32 v140, v51, v114
	v_fmac_f32_e32 v122, v52, v75
	v_fmac_f32_e32 v139, v52, v114
	v_fmac_f32_e32 v121, v53, v75
	v_fmac_f32_e32 v119, v54, v75
	v_fmac_f32_e32 v136, v41, v115
	v_fmac_f32_e32 v138, v42, v74
	v_fmac_f32_e32 v134, v42, v115
	v_fmac_f32_e32 v137, v43, v74
	v_fmac_f32_e32 v151, v43, v115
	v_fmac_f32_e32 v135, v44, v74
	v_fmac_f32_e32 v149, v44, v115
	v_fmac_f32_e32 v133, v45, v74
	v_fmac_f32_e32 v147, v45, v115
	v_fmac_f32_e32 v132, v46, v74
	v_fmac_f32_e32 v143, v46, v115
	v_fmac_f32_e32 v131, v47, v74
	v_fmac_f32_e32 v150, v47, v115
	v_fmac_f32_e32 v130, v48, v74
	v_fmac_f32_e32 v148, v48, v115
	v_fmac_f32_e32 v129, v49, v74
	v_fmac_f32_e32 v146, v49, v115
	v_fmac_f32_e32 v127, v50, v74
	v_fmac_f32_e32 v142, v50, v115
	v_fmac_f32_e32 v124, v51, v74
	v_fmac_f32_e32 v141, v51, v115
	v_fmac_f32_e32 v123, v52, v74
	v_fmac_f32_e32 v140, v52, v115
	v_fmac_f32_e32 v122, v53, v74
	v_fmac_f32_e32 v139, v53, v115
	v_fmac_f32_e32 v121, v54, v74
	v_fmac_f32_e32 v119, v55, v74
	v_fmac_f32_e32 v136, v42, v116
	v_fmac_f32_e32 v138, v43, v28
	v_fmac_f32_e32 v134, v43, v116
	v_fmac_f32_e32 v137, v44, v28
	v_fmac_f32_e32 v151, v44, v116
	v_fmac_f32_e32 v135, v45, v28
	v_fmac_f32_e32 v149, v45, v116
	v_fmac_f32_e32 v133, v46, v28
	v_fmac_f32_e32 v147, v46, v116
	v_fmac_f32_e32 v132, v47, v28
	v_fmac_f32_e32 v143, v47, v116
	v_fmac_f32_e32 v131, v48, v28
	v_fmac_f32_e32 v150, v48, v116
	v_fmac_f32_e32 v130, v49, v28
	v_fmac_f32_e32 v148, v49, v116
	v_fmac_f32_e32 v129, v50, v28
	v_fmac_f32_e32 v146, v50, v116
	v_fmac_f32_e32 v127, v51, v28
	v_fmac_f32_e32 v142, v51, v116
	v_fmac_f32_e32 v124, v52, v28
	v_fmac_f32_e32 v141, v52, v116
	v_fmac_f32_e32 v123, v53, v28
	v_fmac_f32_e32 v140, v53, v116
	v_fmac_f32_e32 v122, v54, v28
	v_fmac_f32_e32 v139, v54, v116
	v_fmac_f32_e32 v121, v55, v28
	v_fmac_f32_e32 v119, v56, v28
	v_fmac_f32_e32 v136, v43, v117
	v_fmac_f32_e32 v138, v44, v29
	v_fmac_f32_e32 v134, v44, v117
	v_fmac_f32_e32 v137, v45, v29
	v_fmac_f32_e32 v151, v45, v117
	v_fmac_f32_e32 v135, v46, v29
	v_fmac_f32_e32 v149, v46, v117
	v_fmac_f32_e32 v133, v47, v29
	v_fmac_f32_e32 v147, v47, v117
	v_fmac_f32_e32 v132, v48, v29
	v_fmac_f32_e32 v143, v48, v117
	v_fmac_f32_e32 v131, v49, v29
	v_fmac_f32_e32 v150, v49, v117
	v_fmac_f32_e32 v130, v50, v29
	v_fmac_f32_e32 v148, v50, v117
	v_fmac_f32_e32 v129, v51, v29
	v_fmac_f32_e32 v146, v51, v117
	v_fmac_f32_e32 v127, v52, v29
	v_fmac_f32_e32 v142, v52, v117
	v_fmac_f32_e32 v124, v53, v29
	v_fmac_f32_e32 v141, v53, v117
	v_fmac_f32_e32 v123, v54, v29
	v_fmac_f32_e32 v140, v54, v117
	v_fmac_f32_e32 v122, v55, v29
	v_fmac_f32_e32 v139, v55, v117
	v_fmac_f32_e32 v121, v56, v29
	v_fmac_f32_e32 v119, v57, v29
	v_fmac_f32_e32 v136, v44, v120
	v_fmac_f32_e32 v138, v45, v106
	v_fmac_f32_e32 v134, v45, v120
	v_fmac_f32_e32 v137, v46, v106
	v_fmac_f32_e32 v151, v46, v120
	v_fmac_f32_e32 v135, v47, v106
	v_fmac_f32_e32 v149, v47, v120
	v_fmac_f32_e32 v133, v48, v106
	v_fmac_f32_e32 v147, v48, v120
	v_fmac_f32_e32 v132, v49, v106
	v_fmac_f32_e32 v143, v49, v120
	v_fmac_f32_e32 v131, v50, v106
	v_fmac_f32_e32 v150, v50, v120
	v_fmac_f32_e32 v130, v51, v106
	v_fmac_f32_e32 v148, v51, v120
	v_fmac_f32_e32 v129, v52, v106
	v_fmac_f32_e32 v146, v52, v120
	v_fmac_f32_e32 v127, v53, v106
	v_fmac_f32_e32 v142, v53, v120
	v_fmac_f32_e32 v124, v54, v106
	v_fmac_f32_e32 v141, v54, v120
	v_fmac_f32_e32 v123, v55, v106
	v_fmac_f32_e32 v140, v55, v120
	v_fmac_f32_e32 v122, v56, v106
	v_fmac_f32_e32 v139, v56, v120
	v_fmac_f32_e32 v121, v57, v106
	v_fmac_f32_e32 v119, v58, v106
	s_waitcnt vmcnt(7)
; __device__ __forceinline__ float bf2f(unsigned short h) { return __uint_as_float(((unsigned)h) << 16); }
; template <int T> __device__ __forceinline__ float conv_tok(const float (&w)[31], const float (&vin)[62], float bias) {
;   float s = bias;
;   #pragma unroll
;   for (int k = 0; k < 31; ++k) s = fmaf(w[k], vin[T + k], s);
;   return s;
; }
; template <int... Ts> __device__ __forceinline__ void conv_all(float (&a)[32], const float (&w)[31], const float (&vin)[62], float bias, std::integer_sequence<int, Ts...>) {
;   ((a[Ts] = conv_tok<Ts>(w, vin, bias)), ...);
; __global__ void __launch_bounds__(512) fwd_megakernel(Params p) {
;     ...
;           const int i2c = min(i2, LTOK - 2 - s0);
;           float v = bf2f(ub[i2c * CONVC]);
;           vin[i2] = (s0 + 1 + i2 >= LTOK) ? 0.f : v;
	v_lshlrev_b32_e32 v106, 16, v126
	v_fmac_f32_e32 v136, v45, v125
	v_fmac_f32_e32 v134, v46, v125
	v_fmac_f32_e32 v151, v47, v125
	v_fmac_f32_e32 v149, v48, v125
	v_fmac_f32_e32 v147, v49, v125
	v_fmac_f32_e32 v143, v50, v125
	v_fmac_f32_e32 v150, v51, v125
	v_fmac_f32_e32 v148, v52, v125
	v_fmac_f32_e32 v146, v53, v125
	v_fmac_f32_e32 v142, v54, v125
	v_fmac_f32_e32 v141, v55, v125
	v_fmac_f32_e32 v140, v56, v125
	v_fmac_f32_e32 v139, v57, v125
	v_cndmask_b32_e32 v106, 0, v106, vcc
	v_fmac_f32_e32 v139, v58, v106
	v_fmac_f32_e32 v140, v57, v106
	v_fmac_f32_e32 v141, v56, v106
	v_fmac_f32_e32 v142, v55, v106
	v_fmac_f32_e32 v146, v54, v106
	v_fmac_f32_e32 v148, v53, v106
	v_fmac_f32_e32 v150, v52, v106
	v_fmac_f32_e32 v143, v51, v106
	v_fmac_f32_e32 v147, v50, v106
	v_fmac_f32_e32 v149, v49, v106
	v_fmac_f32_e32 v151, v48, v106
	v_fmac_f32_e32 v134, v47, v106
	v_fmac_f32_e32 v136, v46, v106
	s_waitcnt vmcnt(6)
	v_lshlrev_b32_e32 v106, 16, v128
	v_cndmask_b32_e64 v106, 0, v106, s[4:5]
	v_fmac_f32_e32 v140, v58, v106
	v_fmac_f32_e32 v141, v57, v106
	v_fmac_f32_e32 v142, v56, v106
	v_fmac_f32_e32 v146, v55, v106
	v_fmac_f32_e32 v148, v54, v106
	v_fmac_f32_e32 v150, v53, v106
	v_fmac_f32_e32 v143, v52, v106
	v_fmac_f32_e32 v147, v51, v106
	v_fmac_f32_e32 v149, v50, v106
	v_fmac_f32_e32 v151, v49, v106
	v_fmac_f32_e32 v134, v48, v106
	v_fmac_f32_e32 v136, v47, v106
	s_waitcnt vmcnt(5)
	v_lshlrev_b32_e32 v106, 16, v152
	v_cndmask_b32_e64 v106, 0, v106, s[6:7]
	v_fmac_f32_e32 v137, v47, v107
	v_fmac_f32_e32 v141, v58, v106
	v_fmac_f32_e32 v142, v57, v106
	v_fmac_f32_e32 v146, v56, v106
	v_fmac_f32_e32 v148, v55, v106
	v_fmac_f32_e32 v150, v54, v106
	v_fmac_f32_e32 v143, v53, v106
	v_fmac_f32_e32 v147, v52, v106
	v_fmac_f32_e32 v149, v51, v106
	v_fmac_f32_e32 v151, v50, v106
	v_fmac_f32_e32 v134, v49, v106
	v_fmac_f32_e32 v136, v48, v106
	s_waitcnt vmcnt(4)
	v_lshlrev_b32_e32 v106, 16, v153
	v_fmac_f32_e32 v135, v48, v107
	v_fmac_f32_e32 v137, v48, v108
	v_cndmask_b32_e64 v106, 0, v106, s[8:9]
	v_fmac_f32_e32 v133, v49, v107
	v_fmac_f32_e32 v135, v49, v108
	v_fmac_f32_e32 v137, v49, v109
	v_fmac_f32_e32 v142, v58, v106
	v_fmac_f32_e32 v146, v57, v106
	v_fmac_f32_e32 v148, v56, v106
	v_fmac_f32_e32 v150, v55, v106
	v_fmac_f32_e32 v143, v54, v106
	v_fmac_f32_e32 v147, v53, v106
	v_fmac_f32_e32 v149, v52, v106
	v_fmac_f32_e32 v151, v51, v106
	v_fmac_f32_e32 v134, v50, v106
	v_fmac_f32_e32 v136, v49, v106
	s_waitcnt vmcnt(3)
	v_lshlrev_b32_e32 v106, 16, v156
	v_fmac_f32_e32 v132, v50, v107
	v_fmac_f32_e32 v133, v50, v108
	v_fmac_f32_e32 v135, v50, v109
	v_fmac_f32_e32 v137, v50, v110
	v_cndmask_b32_e64 v106, 0, v106, s[0:1]
	v_fmac_f32_e32 v131, v51, v107
	v_fmac_f32_e32 v132, v51, v108
	v_fmac_f32_e32 v133, v51, v109
	v_fmac_f32_e32 v135, v51, v110
	v_fmac_f32_e32 v137, v51, v111
	s_cmpk_lt_u32 s41, 0x7d7
	v_fmac_f32_e32 v146, v58, v106
	v_fmac_f32_e32 v148, v57, v106
	v_fmac_f32_e32 v150, v56, v106
	v_fmac_f32_e32 v143, v55, v106
	v_fmac_f32_e32 v147, v54, v106
	v_fmac_f32_e32 v149, v53, v106
	v_fmac_f32_e32 v151, v52, v106
	v_fmac_f32_e32 v134, v51, v106
	v_fmac_f32_e32 v136, v50, v106
	s_waitcnt vmcnt(2)
	v_lshlrev_b32_e32 v106, 16, v157
	v_fmac_f32_e32 v130, v52, v107
	v_fmac_f32_e32 v131, v52, v108
	v_fmac_f32_e32 v132, v52, v109
	v_fmac_f32_e32 v133, v52, v110
	v_fmac_f32_e32 v135, v52, v111
	v_fmac_f32_e32 v137, v52, v112
	v_cndmask_b32_e64 v106, 0, v106, s[12:13]
	s_cselect_b64 vcc, -1, 0
	s_min_u32 s0, s42, 57
	v_fmac_f32_e32 v129, v53, v107
	v_fmac_f32_e32 v130, v53, v108
	v_fmac_f32_e32 v131, v53, v109
	v_fmac_f32_e32 v132, v53, v110
	v_fmac_f32_e32 v133, v53, v111
	v_fmac_f32_e32 v135, v53, v112
	v_fmac_f32_e32 v137, v53, v113
	v_fmac_f32_e32 v148, v58, v106
	v_fmac_f32_e32 v150, v57, v106
	v_fmac_f32_e32 v143, v56, v106
	v_fmac_f32_e32 v147, v55, v106
	v_fmac_f32_e32 v149, v54, v106
	v_fmac_f32_e32 v151, v53, v106
	v_fmac_f32_e32 v134, v52, v106
	v_fmac_f32_e32 v136, v51, v106
	s_waitcnt vmcnt(1)
	v_lshlrev_b32_e32 v106, 16, v158
	s_lshl_b32 s10, s0, 10
	v_fmac_f32_e32 v127, v54, v107
	v_fmac_f32_e32 v129, v54, v108
	v_fmac_f32_e32 v130, v54, v109
	v_fmac_f32_e32 v131, v54, v110
	v_fmac_f32_e32 v132, v54, v111
	v_fmac_f32_e32 v133, v54, v112
	v_fmac_f32_e32 v135, v54, v113
	v_fmac_f32_e32 v137, v54, v114
	v_cndmask_b32_e64 v106, 0, v106, s[14:15]
	s_cmpk_lt_u32 s41, 0x7d6
	v_fmac_f32_e32 v138, v46, v107
	v_fmac_f32_e32 v124, v55, v107
	v_fmac_f32_e32 v127, v55, v108
	v_fmac_f32_e32 v129, v55, v109
	v_fmac_f32_e32 v130, v55, v110
	v_fmac_f32_e32 v131, v55, v111
	v_fmac_f32_e32 v132, v55, v112
	v_fmac_f32_e32 v133, v55, v113
	v_fmac_f32_e32 v135, v55, v114
	v_fmac_f32_e32 v137, v55, v115
	v_fmac_f32_e32 v123, v56, v107
	v_fmac_f32_e32 v122, v57, v107
	v_fmac_f32_e32 v150, v58, v106
	v_fmac_f32_e32 v143, v57, v106
	v_fmac_f32_e32 v147, v56, v106
	v_fmac_f32_e32 v149, v55, v106
	v_fmac_f32_e32 v151, v54, v106
	v_fmac_f32_e32 v134, v53, v106
	v_fmac_f32_e32 v136, v52, v106
	s_waitcnt vmcnt(0)
; __device__ __forceinline__ float bf2f(unsigned short h) { return __uint_as_float(((unsigned)h) << 16); }
; __global__ void __launch_bounds__(512) fwd_megakernel(Params p) {
;     ...
;         float vin[62];
;         #pragma unroll
;         for (int i2 = 0; i2 < 62; ++i2) {
;           const int i2c = min(i2, LTOK - 2 - s0);
;           float v = bf2f(ub[i2c * CONVC]);
;           vin[i2] = (s0 + 1 + i2 >= LTOK) ? 0.f : v;
;         }
;         float a[32];
;         conv_all(a, w, vin, cbias, std::make_integer_sequence<int, 32>{});
;         #pragma unroll
;         for (int t = 0; t < 32; ++t) cbuf[t * CONVC + c] = a[t];
	v_lshlrev_b32_e32 v106, 16, v154
	s_cselect_b64 s[6:7], -1, 0
	s_min_u32 s0, s42, 58
	v_fmac_f32_e32 v138, v47, v108
	v_fmac_f32_e32 v124, v56, v108
	v_fmac_f32_e32 v127, v56, v109
	v_fmac_f32_e32 v129, v56, v110
	v_fmac_f32_e32 v130, v56, v111
	v_fmac_f32_e32 v131, v56, v112
	v_fmac_f32_e32 v132, v56, v113
	v_fmac_f32_e32 v133, v56, v114
	v_fmac_f32_e32 v135, v56, v115
	v_fmac_f32_e32 v137, v56, v116
	v_fmac_f32_e32 v123, v57, v108
	v_fmac_f32_e32 v121, v58, v107
	v_fmac_f32_e32 v122, v58, v108
	v_cndmask_b32_e32 v108, 0, v106, vcc
	v_lshl_add_u64 v[106:107], v[26:27], 0, s[10:11]
	s_lshl_b32 s10, s0, 10
	v_fmac_f32_e32 v124, v57, v109
	v_fmac_f32_e32 v127, v57, v110
	v_fmac_f32_e32 v129, v57, v111
	v_fmac_f32_e32 v130, v57, v112
	v_fmac_f32_e32 v131, v57, v113
	v_fmac_f32_e32 v132, v57, v114
	v_fmac_f32_e32 v133, v57, v115
	v_fmac_f32_e32 v135, v57, v116
	v_fmac_f32_e32 v137, v57, v117
	s_cmpk_lt_u32 s41, 0x7d5
	v_fmac_f32_e32 v123, v58, v109
	v_fmac_f32_e32 v124, v58, v110
	v_fmac_f32_e32 v127, v58, v111
	v_fmac_f32_e32 v129, v58, v112
	v_fmac_f32_e32 v130, v58, v113
	v_fmac_f32_e32 v131, v58, v114
	v_fmac_f32_e32 v132, v58, v115
	v_fmac_f32_e32 v133, v58, v116
	v_fmac_f32_e32 v135, v58, v117
	v_fmac_f32_e32 v137, v58, v120
	ds_write2st64_b32 v62, v121, v122 offset0:48 offset1:56
	ds_write2st64_b32 v62, v123, v124 offset0:64 offset1:72
	ds_write2st64_b32 v62, v127, v129 offset0:80 offset1:88
	ds_write2st64_b32 v62, v130, v131 offset0:96 offset1:104
	ds_write2st64_b32 v62, v132, v133 offset0:112 offset1:120
	ds_write2st64_b32 v62, v135, v137 offset0:128 offset1:136
	s_cselect_b64 vcc, -1, 0
	s_min_u32 s0, s42, 59
	v_fmac_f32_e32 v143, v58, v108
	v_fmac_f32_e32 v147, v57, v108
	v_fmac_f32_e32 v149, v56, v108
	v_fmac_f32_e32 v151, v55, v108
	v_fmac_f32_e32 v134, v54, v108
	v_fmac_f32_e32 v136, v53, v108
	global_load_ushort v108, v[106:107], off
	v_lshl_add_u64 v[106:107], v[26:27], 0, s[10:11]
	s_lshl_b32 s10, s0, 10
	s_cmpk_lt_u32 s41, 0x7d4
	s_cselect_b64 s[0:1], -1, 0
	s_min_u32 s4, s42, 60
	v_fmac_f32_e32 v138, v48, v109
	global_load_ushort v109, v[106:107], off
	v_lshl_add_u64 v[106:107], v[26:27], 0, s[10:11]
	s_lshl_b32 s10, s4, 10
	s_cmpk_lt_u32 s41, 0x7d3
	v_fmac_f32_e32 v138, v49, v110
	global_load_ushort v110, v[106:107], off
	s_cselect_b64 s[4:5], -1, 0
	s_min_u32 s8, s42, 61
	v_lshl_add_u64 v[106:107], v[26:27], 0, s[10:11]
	s_lshl_b32 s10, s8, 10
	global_load_ushort v106, v[106:107], off
	v_lshl_add_u64 v[26:27], v[26:27], 0, s[10:11]
	global_load_ushort v26, v[26:27], off
	v_lshlrev_b32_e32 v27, 16, v100
	v_fmac_f32_e32 v103, v32, v27
	v_fmac_f32_e32 v104, v31, v27
	v_fmac_f32_e32 v105, v30, v27
	v_fmac_f32_e32 v118, v60, v27
	v_fma_f32 v27, v59, v27, v61
	v_fmac_f32_e32 v27, v60, v102
	v_fmac_f32_e32 v118, v30, v102
	v_fmac_f32_e32 v27, v30, v101
	v_fmac_f32_e32 v105, v31, v102
	v_fmac_f32_e32 v118, v31, v101
	v_fmac_f32_e32 v27, v31, v99
	v_fmac_f32_e32 v104, v32, v102
	v_fmac_f32_e32 v105, v32, v101
	v_fmac_f32_e32 v118, v32, v99
	v_fmac_f32_e32 v27, v32, v98
	v_fmac_f32_e32 v103, v33, v102
	v_fmac_f32_e32 v104, v33, v101
	v_fmac_f32_e32 v105, v33, v99
	v_fmac_f32_e32 v118, v33, v98
	v_fmac_f32_e32 v27, v33, v97
	v_fmac_f32_e32 v103, v34, v101
	v_fmac_f32_e32 v104, v34, v99
	v_fmac_f32_e32 v105, v34, v98
	v_fmac_f32_e32 v118, v34, v97
	v_fmac_f32_e32 v27, v34, v96
	v_fmac_f32_e32 v103, v35, v99
	v_fmac_f32_e32 v104, v35, v98
	v_fmac_f32_e32 v105, v35, v97
	v_fmac_f32_e32 v118, v35, v96
	v_fmac_f32_e32 v27, v35, v95
	v_fmac_f32_e32 v103, v36, v98
	v_fmac_f32_e32 v104, v36, v97
	v_fmac_f32_e32 v105, v36, v96
	v_fmac_f32_e32 v118, v36, v95
	v_fmac_f32_e32 v27, v36, v94
	v_fmac_f32_e32 v103, v37, v97
	v_fmac_f32_e32 v104, v37, v96
	v_fmac_f32_e32 v105, v37, v95
	v_fmac_f32_e32 v118, v37, v94
	v_fmac_f32_e32 v27, v37, v93
	v_fmac_f32_e32 v103, v38, v96
	v_fmac_f32_e32 v104, v38, v95
	v_fmac_f32_e32 v105, v38, v94
	v_fmac_f32_e32 v118, v38, v93
	v_fmac_f32_e32 v27, v38, v92
	v_fmac_f32_e32 v103, v39, v95
	v_fmac_f32_e32 v104, v39, v94
	v_fmac_f32_e32 v105, v39, v93
	v_fmac_f32_e32 v118, v39, v92
	v_fmac_f32_e32 v27, v39, v91
	v_fmac_f32_e32 v103, v40, v94
	v_fmac_f32_e32 v104, v40, v93
	v_fmac_f32_e32 v105, v40, v92
	v_fmac_f32_e32 v118, v40, v91
	v_fmac_f32_e32 v27, v40, v90
	v_fmac_f32_e32 v103, v41, v93
	v_fmac_f32_e32 v104, v41, v92
	v_fmac_f32_e32 v105, v41, v91
	v_fmac_f32_e32 v118, v41, v90
	v_fmac_f32_e32 v27, v41, v89
	v_fmac_f32_e32 v103, v42, v92
	v_fmac_f32_e32 v104, v42, v91
	v_fmac_f32_e32 v105, v42, v90
	v_fmac_f32_e32 v118, v42, v89
	v_fmac_f32_e32 v27, v42, v88
	v_fmac_f32_e32 v103, v43, v91
	v_fmac_f32_e32 v104, v43, v90
	v_fmac_f32_e32 v105, v43, v89
	v_fmac_f32_e32 v118, v43, v88
	v_fmac_f32_e32 v27, v43, v87
	v_fmac_f32_e32 v103, v44, v90
	v_fmac_f32_e32 v104, v44, v89
	v_fmac_f32_e32 v105, v44, v88
	v_fmac_f32_e32 v118, v44, v87
	v_fmac_f32_e32 v27, v44, v86
	v_fmac_f32_e32 v103, v45, v89
	v_fmac_f32_e32 v104, v45, v88
	v_fmac_f32_e32 v105, v45, v87
	v_fmac_f32_e32 v118, v45, v86
	v_fmac_f32_e32 v27, v45, v85
	v_fmac_f32_e32 v103, v46, v88
	v_fmac_f32_e32 v104, v46, v87
	v_fmac_f32_e32 v105, v46, v86
	v_fmac_f32_e32 v118, v46, v85
	v_fmac_f32_e32 v27, v46, v84
	v_fmac_f32_e32 v103, v47, v87
	v_fmac_f32_e32 v104, v47, v86
	v_fmac_f32_e32 v105, v47, v85
	v_fmac_f32_e32 v118, v47, v84
	v_fmac_f32_e32 v27, v47, v83
	v_fmac_f32_e32 v103, v48, v86
	v_fmac_f32_e32 v104, v48, v85
	v_fmac_f32_e32 v105, v48, v84
	v_fmac_f32_e32 v118, v48, v83
	v_fmac_f32_e32 v27, v48, v82
	v_fmac_f32_e32 v103, v49, v85
	v_fmac_f32_e32 v104, v49, v84
	v_fmac_f32_e32 v105, v49, v83
	v_fmac_f32_e32 v118, v49, v82
	v_fmac_f32_e32 v27, v49, v81
; __global__ void __launch_bounds__(512) fwd_megakernel(Params p) {
;     ...
;         conv_all(a, w, vin, cbias, std::make_integer_sequence<int, 32>{});
;         #pragma unroll
;         for (int t = 0; t < 32; ++t) cbuf[t * CONVC + c] = a[t];
;         __syncthreads();
;         #pragma unroll
;         for (int tt = 0; tt < 4; ++tt) {
;           const int t = wid * 4 + tt;
;           f32x4 x0 = *reinterpret_cast<const f32x4*>(cbuf + t * CONVC + lane * 4), x1 = *reinterpret_cast<const f32x4*>(cbuf + t * CONVC + 256 + lane * 4);
;           float s = (x0[0] + x0[1]) + (x0[2] + x0[3]) + (x1[0] + x1[1]) + (x1[2] + x1[3]);
;           #pragma unroll
;           for (int sh = 32; sh >= 1; sh >>= 1) s += __shfl_xor(s, sh);
;           const float mean = s * (1.f / CONVC);
;           float q2 = 0.f;
;           #pragma unroll
;           for (int i = 0; i < 4; ++i) { x0[i] -= mean; x1[i] -= mean; q2 += x0[i] * x0[i] + x1[i] * x1[i]; }
;           #pragma unroll
;           for (int sh = 32; sh >= 1; sh >>= 1) q2 += __shfl_xor(q2, sh);
	v_fmac_f32_e32 v138, v50, v111
	v_fmac_f32_e32 v103, v50, v84
	v_fmac_f32_e32 v104, v50, v83
	v_fmac_f32_e32 v105, v50, v82
	v_fmac_f32_e32 v118, v50, v81
	v_fmac_f32_e32 v27, v50, v80
	v_fmac_f32_e32 v138, v51, v112
	v_fmac_f32_e32 v103, v51, v83
	v_fmac_f32_e32 v104, v51, v82
	v_fmac_f32_e32 v105, v51, v81
	v_fmac_f32_e32 v118, v51, v80
	v_fmac_f32_e32 v27, v51, v79
	v_fmac_f32_e32 v138, v52, v113
	v_fmac_f32_e32 v103, v52, v82
	v_fmac_f32_e32 v104, v52, v81
	v_fmac_f32_e32 v105, v52, v80
	v_fmac_f32_e32 v118, v52, v79
	v_fmac_f32_e32 v27, v52, v78
	v_fmac_f32_e32 v138, v53, v114
	v_fmac_f32_e32 v103, v53, v81
	v_fmac_f32_e32 v104, v53, v80
	v_fmac_f32_e32 v105, v53, v79
	v_fmac_f32_e32 v118, v53, v78
	v_fmac_f32_e32 v27, v53, v77
	v_fmac_f32_e32 v138, v54, v115
	v_fmac_f32_e32 v103, v54, v80
	v_fmac_f32_e32 v104, v54, v79
	v_fmac_f32_e32 v105, v54, v78
	v_fmac_f32_e32 v118, v54, v77
	v_fmac_f32_e32 v27, v54, v76
	v_fmac_f32_e32 v138, v55, v116
	v_fmac_f32_e32 v103, v55, v79
	v_fmac_f32_e32 v104, v55, v78
	v_fmac_f32_e32 v105, v55, v77
	v_fmac_f32_e32 v118, v55, v76
	v_fmac_f32_e32 v27, v55, v75
	v_fmac_f32_e32 v138, v56, v117
	v_fmac_f32_e32 v103, v56, v78
	v_fmac_f32_e32 v104, v56, v77
	v_fmac_f32_e32 v105, v56, v76
	v_fmac_f32_e32 v118, v56, v75
	v_fmac_f32_e32 v27, v56, v74
	v_fmac_f32_e32 v138, v57, v120
	v_fmac_f32_e32 v103, v57, v77
	v_fmac_f32_e32 v104, v57, v76
	v_fmac_f32_e32 v105, v57, v75
	v_fmac_f32_e32 v118, v57, v74
	v_fmac_f32_e32 v27, v57, v28
	v_fmac_f32_e32 v138, v58, v125
	v_fmac_f32_e32 v103, v58, v76
	v_fmac_f32_e32 v104, v58, v75
	v_fmac_f32_e32 v105, v58, v74
	v_fmac_f32_e32 v118, v58, v28
	v_fmac_f32_e32 v27, v58, v29
	ds_write2st64_b32 v62, v138, v139 offset0:144 offset1:152
	ds_write2st64_b32 v62, v140, v141 offset0:160 offset1:168
	ds_write2st64_b32 v62, v142, v146 offset0:176 offset1:184
	ds_write2st64_b32 v62, v148, v150 offset0:192 offset1:200
	ds_write2st64_b32 v62, v103, v104 offset1:8
	ds_write2st64_b32 v62, v105, v118 offset0:16 offset1:24
	ds_write2st64_b32 v62, v27, v119 offset0:32 offset1:40
	s_waitcnt vmcnt(4)
	v_lshlrev_b32_e32 v27, 16, v108
	v_cndmask_b32_e64 v27, 0, v27, s[6:7]
	v_fmac_f32_e32 v147, v58, v27
	v_fmac_f32_e32 v149, v57, v27
	v_fmac_f32_e32 v151, v56, v27
	v_fmac_f32_e32 v134, v55, v27
	v_fmac_f32_e32 v136, v54, v27
	s_waitcnt vmcnt(3)
	v_lshlrev_b32_e32 v27, 16, v109
	v_cndmask_b32_e32 v27, 0, v27, vcc
	v_fmac_f32_e32 v149, v58, v27
	v_fmac_f32_e32 v151, v57, v27
	v_fmac_f32_e32 v134, v56, v27
	v_fmac_f32_e32 v136, v55, v27
	s_waitcnt vmcnt(2)
	v_lshlrev_b32_e32 v27, 16, v110
	v_cndmask_b32_e64 v27, 0, v27, s[0:1]
	s_cmpk_lt_u32 s41, 0x7d2
	v_fmac_f32_e32 v151, v58, v27
	v_fmac_f32_e32 v134, v57, v27
	v_fmac_f32_e32 v136, v56, v27
	s_waitcnt vmcnt(1)
	v_lshlrev_b32_e32 v27, 16, v106
	v_cndmask_b32_e64 v27, 0, v27, s[4:5]
	s_waitcnt vmcnt(0)
	v_lshlrev_b32_e32 v26, 16, v26
	s_cselect_b64 vcc, -1, 0
	v_fmac_f32_e32 v136, v57, v27
	v_cndmask_b32_e32 v26, 0, v26, vcc
	v_fmac_f32_e32 v134, v58, v27
	v_fmac_f32_e32 v136, v58, v26
	ds_write2st64_b32 v62, v143, v147 offset0:208 offset1:216
	ds_write2st64_b32 v62, v149, v151 offset0:224 offset1:232
	s_lshl_b64 s[0:1], s[2:3], 11
	ds_write2st64_b32 v62, v134, v136 offset0:240 offset1:248
	s_waitcnt lgkmcnt(0)
	s_barrier
	ds_read_b128 v[74:77], v63
	ds_read_b128 v[78:81], v63 offset:1024
	s_or_b32 s0, s0, s41
	v_lshl_add_u64 v[26:27], s[0:1], 0, v[144:145]
	v_lshl_add_u64 v[28:29], s[0:1], 0, v[16:17]
	v_lshl_add_u64 v[82:83], s[0:1], 0, v[22:23]
	v_lshl_add_u64 v[84:85], s[0:1], 0, v[24:25]
	v_lshlrev_b64 v[26:27], 11, v[26:27]
	v_lshlrev_b64 v[28:29], 11, v[28:29]
	v_lshlrev_b64 v[82:83], 11, v[82:83]
	v_lshlrev_b64 v[84:85], 11, v[84:85]
	v_lshl_add_u64 v[86:87], v[20:21], 0, v[26:27]
	v_lshl_add_u64 v[88:89], v[20:21], 0, v[28:29]
	v_lshl_add_u64 v[28:29], v[20:21], 0, v[82:83]
	v_lshl_add_u64 v[26:27], v[20:21], 0, v[84:85]
	s_waitcnt lgkmcnt(1)
	v_mov_b32_e32 v82, v75
	v_mov_b32_e32 v83, v76
	v_mov_b32_e32 v84, v74
	v_mov_b32_e32 v85, v77
	s_waitcnt lgkmcnt(0)
	v_mov_b32_e32 v90, v80
	v_mov_b32_e32 v91, v78
	v_mov_b32_e32 v92, v81
	v_mov_b32_e32 v93, v79
	v_pk_add_f32 v[82:83], v[82:83], v[84:85]
	v_pk_add_f32 v[84:85], v[90:91], v[92:93]
	v_add_f32_e32 v82, v82, v83
	v_add_f32_e32 v82, v82, v85
	v_add_f32_e32 v82, v84, v82
	s_add_i32 s40, s40, s94
	s_add_i32 s29, s29, s30
	s_cmpk_gt_i32 s40, 0xbff
	s_waitcnt lgkmcnt(0)
	s_nop 1
	v_add_f32_dpp v82, v82, v82 quad_perm:[1,0,3,2] row_mask:0xf bank_mask:0xf
	s_nop 1
	v_add_f32_dpp v82, v82, v82 quad_perm:[2,3,0,1] row_mask:0xf bank_mask:0xf
	s_nop 1
	v_add_f32_dpp v82, v82, v82 row_half_mirror row_mask:0xf bank_mask:0xf
	s_nop 1
	v_add_f32_dpp v82, v82, v82 row_mirror row_mask:0xf bank_mask:0xf
	v_mov_b32_e32 v83, v82
	s_nop 1
	v_permlane16_swap_b32_e32 v82, v83
	v_add_f32_e32 v82, v82, v83
	v_mov_b32_e32 v83, v82
	s_nop 1
	v_permlane32_swap_b32_e32 v82, v83
	v_add_f32_e32 v82, v82, v83
	v_mul_f32_e32 v82, 0x3b000000, v82
	v_pk_add_f32 v[78:79], v[78:79], v[82:83] op_sel_hi:[1,0] neg_lo:[0,1] neg_hi:[0,1]
	v_pk_add_f32 v[74:75], v[74:75], v[82:83] op_sel_hi:[1,0] neg_lo:[0,1] neg_hi:[0,1]
	v_pk_add_f32 v[76:77], v[76:77], v[82:83] op_sel_hi:[1,0] neg_lo:[0,1] neg_hi:[0,1]
	v_pk_add_f32 v[80:81], v[80:81], v[82:83] op_sel_hi:[1,0] neg_lo:[0,1] neg_hi:[0,1]
	v_pk_mul_f32 v[82:83], v[78:79], v[78:79]
	v_pk_mul_f32 v[84:85], v[80:81], v[80:81]
	v_pk_fma_f32 v[82:83], v[74:75], v[74:75], v[82:83]
	v_pk_fma_f32 v[84:85], v[76:77], v[76:77], v[84:85]
	v_add_f32_e32 v82, v82, v83
	v_add_f32_e32 v82, v82, v84
	v_add_f32_e32 v82, v82, v85
	s_waitcnt lgkmcnt(0)
; __device__ __forceinline__ float siluf_(float x) { return x * sigmoidf_(x); }
; __global__ void __launch_bounds__(512) fwd_megakernel(Params p) {
;     ...
;           const float mean = s * (1.f / CONVC);
;           float q2 = 0.f;
;           #pragma unroll
;           for (int i = 0; i < 4; ++i) { x0[i] -= mean; x1[i] -= mean; q2 += x0[i] * x0[i] + x1[i] * x1[i]; }
;           #pragma unroll
;           for (int sh = 32; sh >= 1; sh >>= 1) q2 += __shfl_xor(q2, sh);
;           const float rstd = rsqrtf(q2 * (1.f / CONVC) + EPS);
;           float y0[4], y1[4];
;           #pragma unroll
;           for (int i = 0; i < 4; ++i) { y0[i] = siluf_(x0[i] * rstd * g0[i] + b0[i]); y1[i] = siluf_(x1[i] * rstd * g1[i] + b1[i]); }
;           bf16* od = p_mix + ((long)b * SEQ + s0 + t) * DM + lane * 4;
;           *reinterpret_cast<u32x2*>(od) = u32x2{cvtpk(y0[0], y0[1]), cvtpk(y0[2], y0[3])};
;           *reinterpret_cast<u32x2*>(od + 256) = u32x2{cvtpk(y1[0], y1[1]), cvtpk(y1[2], y1[3])};
	s_nop 1
	v_add_f32_dpp v82, v82, v82 quad_perm:[1,0,3,2] row_mask:0xf bank_mask:0xf
	s_nop 1
	v_add_f32_dpp v82, v82, v82 quad_perm:[2,3,0,1] row_mask:0xf bank_mask:0xf
	s_nop 1
	v_add_f32_dpp v82, v82, v82 row_half_mirror row_mask:0xf bank_mask:0xf
	s_nop 1
	v_add_f32_dpp v82, v82, v82 row_mirror row_mask:0xf bank_mask:0xf
	v_mov_b32_e32 v83, v82
	s_nop 1
	v_permlane16_swap_b32_e32 v82, v83
	v_add_f32_e32 v82, v82, v83
	v_mov_b32_e32 v83, v82
	s_nop 1
	v_permlane32_swap_b32_e32 v82, v83
	v_add_f32_e32 v82, v82, v83
	v_fmamk_f32 v82, v82, 0x3b000000, v73
	v_mul_f32_e32 v83, 0x4b800000, v82
	v_cmp_gt_f32_e32 vcc, s31, v82
	s_nop 1
	v_cndmask_b32_e32 v82, v82, v83, vcc
	v_rsq_f32_e32 v82, v82
	s_nop 0
	v_mul_f32_e32 v83, 0x45800000, v82
	v_cndmask_b32_e32 v82, v82, v83, vcc
	v_mul_f32_e32 v74, v82, v74
	v_mul_f32_e32 v75, v82, v75
	v_mul_f32_e32 v78, v82, v78
	v_mul_f32_e32 v79, v82, v79
	v_mul_f32_e32 v76, v82, v76
	v_mul_f32_e32 v80, v82, v80
	v_mul_f32_e32 v77, v82, v77
	v_mul_f32_e32 v81, v82, v81
	v_fma_f32 v74, v12, v74, v8
	v_fma_f32 v75, v13, v75, v9
	v_fma_f32 v78, v4, v78, v0
	v_fma_f32 v79, v5, v79, v1
	v_fma_f32 v76, v14, v76, v10
	v_fma_f32 v80, v6, v80, v2
	v_fma_f32 v77, v15, v77, v11
	v_fma_f32 v81, v7, v81, v3
	v_mul_f32_e32 v82, 0xbfb8aa3b, v74
	v_mul_f32_e32 v84, 0xbfb8aa3b, v75
	v_mul_f32_e32 v83, 0xbfb8aa3b, v78
	v_mul_f32_e32 v85, 0xbfb8aa3b, v79
	v_mul_f32_e32 v90, 0xbfb8aa3b, v76
	v_mul_f32_e32 v91, 0xbfb8aa3b, v80
	v_mul_f32_e32 v92, 0xbfb8aa3b, v77
	v_mul_f32_e32 v93, 0xbfb8aa3b, v81
	v_exp_f32_e32 v82, v82
	v_exp_f32_e32 v84, v84
	v_exp_f32_e32 v83, v83
	v_exp_f32_e32 v85, v85
	v_exp_f32_e32 v90, v90
	v_exp_f32_e32 v91, v91
	v_exp_f32_e32 v92, v92
	v_exp_f32_e32 v93, v93
	v_add_f32_e32 v82, 1.0, v82
	v_add_f32_e32 v84, 1.0, v84
	v_add_f32_e32 v83, 1.0, v83
	v_add_f32_e32 v85, 1.0, v85
	v_add_f32_e32 v90, 1.0, v90
	v_add_f32_e32 v91, 1.0, v91
	v_add_f32_e32 v92, 1.0, v92
	v_add_f32_e32 v93, 1.0, v93
	v_rcp_f32_e32 v82, v82
	v_rcp_f32_e32 v84, v84
	v_rcp_f32_e32 v83, v83
	v_rcp_f32_e32 v85, v85
	v_rcp_f32_e32 v90, v90
	v_rcp_f32_e32 v91, v91
	v_rcp_f32_e32 v92, v92
	v_rcp_f32_e32 v93, v93
	v_mul_f32_e32 v74, v74, v82
	v_mul_f32_e32 v75, v75, v84
	v_mul_f32_e32 v78, v78, v83
	v_mul_f32_e32 v79, v79, v85
	v_mul_f32_e32 v76, v76, v90
	v_mul_f32_e32 v80, v80, v91
	v_mul_f32_e32 v77, v77, v92
	v_mul_f32_e32 v81, v81, v93
	v_cvt_pk_bf16_f32 v74, v74, v75
	v_cvt_pk_bf16_f32 v75, v76, v77
	global_store_dwordx2 v[86:87], v[74:75], off
	v_cvt_pk_bf16_f32 v82, v78, v79
	v_cvt_pk_bf16_f32 v83, v80, v81
	ds_read_b128 v[74:77], v70
	ds_read_b128 v[78:81], v70 offset:1024
	global_store_dwordx2 v[86:87], v[82:83], off offset:512
	s_waitcnt lgkmcnt(1)
	v_mov_b32_e32 v82, v75
	v_mov_b32_e32 v83, v76
	v_mov_b32_e32 v84, v74
	v_mov_b32_e32 v85, v77
	s_waitcnt lgkmcnt(0)
	v_mov_b32_e32 v86, v80
	v_mov_b32_e32 v87, v78
	v_mov_b32_e32 v90, v81
	v_mov_b32_e32 v91, v79
	v_pk_add_f32 v[82:83], v[82:83], v[84:85]
	v_pk_add_f32 v[84:85], v[86:87], v[90:91]
	v_add_f32_e32 v82, v82, v83
	v_add_f32_e32 v82, v82, v85
	v_add_f32_e32 v82, v84, v82
	s_waitcnt lgkmcnt(0)
	s_nop 1
	v_add_f32_dpp v82, v82, v82 quad_perm:[1,0,3,2] row_mask:0xf bank_mask:0xf
	s_nop 1
	v_add_f32_dpp v82, v82, v82 quad_perm:[2,3,0,1] row_mask:0xf bank_mask:0xf
	s_nop 1
	v_add_f32_dpp v82, v82, v82 row_half_mirror row_mask:0xf bank_mask:0xf
	s_nop 1
	v_add_f32_dpp v82, v82, v82 row_mirror row_mask:0xf bank_mask:0xf
	v_mov_b32_e32 v83, v82
	s_nop 1
	v_permlane16_swap_b32_e32 v82, v83
	v_add_f32_e32 v82, v82, v83
	v_mov_b32_e32 v83, v82
	s_nop 1
	v_permlane32_swap_b32_e32 v82, v83
	v_add_f32_e32 v82, v82, v83
	v_mul_f32_e32 v82, 0x3b000000, v82
	v_pk_add_f32 v[78:79], v[78:79], v[82:83] op_sel_hi:[1,0] neg_lo:[0,1] neg_hi:[0,1]
	v_pk_add_f32 v[74:75], v[74:75], v[82:83] op_sel_hi:[1,0] neg_lo:[0,1] neg_hi:[0,1]
	v_pk_add_f32 v[76:77], v[76:77], v[82:83] op_sel_hi:[1,0] neg_lo:[0,1] neg_hi:[0,1]
	v_pk_add_f32 v[80:81], v[80:81], v[82:83] op_sel_hi:[1,0] neg_lo:[0,1] neg_hi:[0,1]
	v_pk_mul_f32 v[82:83], v[78:79], v[78:79]
	v_pk_mul_f32 v[84:85], v[80:81], v[80:81]
	v_pk_fma_f32 v[82:83], v[74:75], v[74:75], v[82:83]
	v_pk_fma_f32 v[84:85], v[76:77], v[76:77], v[84:85]
	v_add_f32_e32 v82, v82, v83
	v_add_f32_e32 v82, v82, v84
	v_add_f32_e32 v82, v82, v85
	s_waitcnt lgkmcnt(0)
; __device__ __forceinline__ float siluf_(float x) { return x * sigmoidf_(x); }
; __global__ void __launch_bounds__(512) fwd_megakernel(Params p) {
;     ...
;           f32x4 x0 = *reinterpret_cast<const f32x4*>(cbuf + t * CONVC + lane * 4), x1 = *reinterpret_cast<const f32x4*>(cbuf + t * CONVC + 256 + lane * 4);
;           float s = (x0[0] + x0[1]) + (x0[2] + x0[3]) + (x1[0] + x1[1]) + (x1[2] + x1[3]);
;           #pragma unroll
;           for (int sh = 32; sh >= 1; sh >>= 1) s += __shfl_xor(s, sh);
;           const float mean = s * (1.f / CONVC);
;           float q2 = 0.f;
;           #pragma unroll
;           for (int i = 0; i < 4; ++i) { x0[i] -= mean; x1[i] -= mean; q2 += x0[i] * x0[i] + x1[i] * x1[i]; }
;           #pragma unroll
;           for (int sh = 32; sh >= 1; sh >>= 1) q2 += __shfl_xor(q2, sh);
;           const float rstd = rsqrtf(q2 * (1.f / CONVC) + EPS);
;           float y0[4], y1[4];
;           #pragma unroll
;           for (int i = 0; i < 4; ++i) { y0[i] = siluf_(x0[i] * rstd * g0[i] + b0[i]); y1[i] = siluf_(x1[i] * rstd * g1[i] + b1[i]); }
;           bf16* od = p_mix + ((long)b * SEQ + s0 + t) * DM + lane * 4;
;           *reinterpret_cast<u32x2*>(od) = u32x2{cvtpk(y0[0], y0[1]), cvtpk(y0[2], y0[3])};
;           *reinterpret_cast<u32x2*>(od + 256) = u32x2{cvtpk(y1[0], y1[1]), cvtpk(y1[2], y1[3])};
	s_nop 1
	v_add_f32_dpp v82, v82, v82 quad_perm:[1,0,3,2] row_mask:0xf bank_mask:0xf
	s_nop 1
	v_add_f32_dpp v82, v82, v82 quad_perm:[2,3,0,1] row_mask:0xf bank_mask:0xf
	s_nop 1
	v_add_f32_dpp v82, v82, v82 row_half_mirror row_mask:0xf bank_mask:0xf
	s_nop 1
	v_add_f32_dpp v82, v82, v82 row_mirror row_mask:0xf bank_mask:0xf
	v_mov_b32_e32 v83, v82
	s_nop 1
	v_permlane16_swap_b32_e32 v82, v83
	v_add_f32_e32 v82, v82, v83
	v_mov_b32_e32 v83, v82
	s_nop 1
	v_permlane32_swap_b32_e32 v82, v83
	v_add_f32_e32 v82, v82, v83
	v_fmamk_f32 v82, v82, 0x3b000000, v73
	v_mul_f32_e32 v83, 0x4b800000, v82
	v_cmp_gt_f32_e32 vcc, s31, v82
	s_nop 1
	v_cndmask_b32_e32 v82, v82, v83, vcc
	v_rsq_f32_e32 v82, v82
	s_nop 0
	v_mul_f32_e32 v83, 0x45800000, v82
	v_cndmask_b32_e32 v82, v82, v83, vcc
	v_mul_f32_e32 v74, v82, v74
	v_mul_f32_e32 v75, v82, v75
	v_mul_f32_e32 v78, v82, v78
	v_mul_f32_e32 v79, v82, v79
	v_mul_f32_e32 v76, v82, v76
	v_mul_f32_e32 v80, v82, v80
	v_mul_f32_e32 v77, v82, v77
	v_mul_f32_e32 v81, v82, v81
	v_fma_f32 v74, v12, v74, v8
	v_fma_f32 v75, v13, v75, v9
	v_fma_f32 v78, v4, v78, v0
	v_fma_f32 v79, v5, v79, v1
	v_fma_f32 v76, v14, v76, v10
	v_fma_f32 v80, v6, v80, v2
	v_fma_f32 v77, v15, v77, v11
	v_fma_f32 v81, v7, v81, v3
	v_mul_f32_e32 v82, 0xbfb8aa3b, v74
	v_mul_f32_e32 v84, 0xbfb8aa3b, v75
	v_mul_f32_e32 v83, 0xbfb8aa3b, v78
	v_mul_f32_e32 v85, 0xbfb8aa3b, v79
	v_mul_f32_e32 v86, 0xbfb8aa3b, v76
	v_mul_f32_e32 v87, 0xbfb8aa3b, v80
	v_mul_f32_e32 v90, 0xbfb8aa3b, v77
	v_mul_f32_e32 v91, 0xbfb8aa3b, v81
	v_exp_f32_e32 v82, v82
	v_exp_f32_e32 v84, v84
	v_exp_f32_e32 v83, v83
	v_exp_f32_e32 v85, v85
	v_exp_f32_e32 v86, v86
	v_exp_f32_e32 v87, v87
	v_exp_f32_e32 v90, v90
	v_exp_f32_e32 v91, v91
	v_add_f32_e32 v82, 1.0, v82
	v_add_f32_e32 v84, 1.0, v84
	v_add_f32_e32 v83, 1.0, v83
	v_add_f32_e32 v85, 1.0, v85
	v_add_f32_e32 v86, 1.0, v86
	v_add_f32_e32 v87, 1.0, v87
	v_add_f32_e32 v90, 1.0, v90
	v_add_f32_e32 v91, 1.0, v91
	v_rcp_f32_e32 v82, v82
	v_rcp_f32_e32 v84, v84
	v_rcp_f32_e32 v83, v83
	v_rcp_f32_e32 v85, v85
	v_rcp_f32_e32 v86, v86
	v_rcp_f32_e32 v87, v87
	v_rcp_f32_e32 v90, v90
	v_rcp_f32_e32 v91, v91
	v_mul_f32_e32 v74, v74, v82
	v_mul_f32_e32 v75, v75, v84
	v_mul_f32_e32 v78, v78, v83
	v_mul_f32_e32 v79, v79, v85
	v_mul_f32_e32 v76, v76, v86
	v_mul_f32_e32 v80, v80, v87
	v_mul_f32_e32 v77, v77, v90
	v_mul_f32_e32 v81, v81, v91
	v_cvt_pk_bf16_f32 v74, v74, v75
	v_cvt_pk_bf16_f32 v75, v76, v77
	global_store_dwordx2 v[88:89], v[74:75], off
	v_cvt_pk_bf16_f32 v82, v78, v79
	v_cvt_pk_bf16_f32 v83, v80, v81
	ds_read_b128 v[74:77], v71
	ds_read_b128 v[78:81], v71 offset:1024
	global_store_dwordx2 v[88:89], v[82:83], off offset:512
	s_waitcnt lgkmcnt(1)
	v_mov_b32_e32 v82, v75
	v_mov_b32_e32 v83, v76
	v_mov_b32_e32 v84, v74
	v_mov_b32_e32 v85, v77
	s_waitcnt lgkmcnt(0)
	v_mov_b32_e32 v86, v80
	v_mov_b32_e32 v87, v78
	v_mov_b32_e32 v88, v81
	v_mov_b32_e32 v89, v79
	v_pk_add_f32 v[82:83], v[82:83], v[84:85]
	v_pk_add_f32 v[84:85], v[86:87], v[88:89]
	v_add_f32_e32 v82, v82, v83
	v_add_f32_e32 v82, v82, v85
	v_add_f32_e32 v82, v84, v82
	s_waitcnt lgkmcnt(0)
	s_nop 1
	v_add_f32_dpp v82, v82, v82 quad_perm:[1,0,3,2] row_mask:0xf bank_mask:0xf
	s_nop 1
	v_add_f32_dpp v82, v82, v82 quad_perm:[2,3,0,1] row_mask:0xf bank_mask:0xf
	s_nop 1
	v_add_f32_dpp v82, v82, v82 row_half_mirror row_mask:0xf bank_mask:0xf
	s_nop 1
	v_add_f32_dpp v82, v82, v82 row_mirror row_mask:0xf bank_mask:0xf
	v_mov_b32_e32 v83, v82
	s_nop 1
	v_permlane16_swap_b32_e32 v82, v83
	v_add_f32_e32 v82, v82, v83
	v_mov_b32_e32 v83, v82
	s_nop 1
	v_permlane32_swap_b32_e32 v82, v83
	v_add_f32_e32 v82, v82, v83
	v_mul_f32_e32 v82, 0x3b000000, v82
	v_pk_add_f32 v[78:79], v[78:79], v[82:83] op_sel_hi:[1,0] neg_lo:[0,1] neg_hi:[0,1]
	v_pk_add_f32 v[74:75], v[74:75], v[82:83] op_sel_hi:[1,0] neg_lo:[0,1] neg_hi:[0,1]
	v_pk_add_f32 v[76:77], v[76:77], v[82:83] op_sel_hi:[1,0] neg_lo:[0,1] neg_hi:[0,1]
	v_pk_add_f32 v[80:81], v[80:81], v[82:83] op_sel_hi:[1,0] neg_lo:[0,1] neg_hi:[0,1]
	v_pk_mul_f32 v[82:83], v[78:79], v[78:79]
	v_pk_mul_f32 v[84:85], v[80:81], v[80:81]
	v_pk_fma_f32 v[82:83], v[74:75], v[74:75], v[82:83]
	v_pk_fma_f32 v[84:85], v[76:77], v[76:77], v[84:85]
	v_add_f32_e32 v82, v82, v83
	v_add_f32_e32 v82, v82, v84
	v_add_f32_e32 v82, v82, v85
	s_waitcnt lgkmcnt(0)
; __device__ __forceinline__ float siluf_(float x) { return x * sigmoidf_(x); }
; __global__ void __launch_bounds__(512) fwd_megakernel(Params p) {
;     ...
;           f32x4 x0 = *reinterpret_cast<const f32x4*>(cbuf + t * CONVC + lane * 4), x1 = *reinterpret_cast<const f32x4*>(cbuf + t * CONVC + 256 + lane * 4);
;           float s = (x0[0] + x0[1]) + (x0[2] + x0[3]) + (x1[0] + x1[1]) + (x1[2] + x1[3]);
;           #pragma unroll
;           for (int sh = 32; sh >= 1; sh >>= 1) s += __shfl_xor(s, sh);
;           const float mean = s * (1.f / CONVC);
;           float q2 = 0.f;
;           #pragma unroll
;           for (int i = 0; i < 4; ++i) { x0[i] -= mean; x1[i] -= mean; q2 += x0[i] * x0[i] + x1[i] * x1[i]; }
;           #pragma unroll
;           for (int sh = 32; sh >= 1; sh >>= 1) q2 += __shfl_xor(q2, sh);
;           const float rstd = rsqrtf(q2 * (1.f / CONVC) + EPS);
;           float y0[4], y1[4];
;           #pragma unroll
;           for (int i = 0; i < 4; ++i) { y0[i] = siluf_(x0[i] * rstd * g0[i] + b0[i]); y1[i] = siluf_(x1[i] * rstd * g1[i] + b1[i]); }
;           bf16* od = p_mix + ((long)b * SEQ + s0 + t) * DM + lane * 4;
;           *reinterpret_cast<u32x2*>(od) = u32x2{cvtpk(y0[0], y0[1]), cvtpk(y0[2], y0[3])};
;           *reinterpret_cast<u32x2*>(od + 256) = u32x2{cvtpk(y1[0], y1[1]), cvtpk(y1[2], y1[3])};
;         }
;         __syncthreads();
	s_nop 1
	v_add_f32_dpp v82, v82, v82 quad_perm:[1,0,3,2] row_mask:0xf bank_mask:0xf
	s_nop 1
	v_add_f32_dpp v82, v82, v82 quad_perm:[2,3,0,1] row_mask:0xf bank_mask:0xf
	s_nop 1
	v_add_f32_dpp v82, v82, v82 row_half_mirror row_mask:0xf bank_mask:0xf
	s_nop 1
	v_add_f32_dpp v82, v82, v82 row_mirror row_mask:0xf bank_mask:0xf
	v_mov_b32_e32 v83, v82
	s_nop 1
	v_permlane16_swap_b32_e32 v82, v83
	v_add_f32_e32 v82, v82, v83
	v_mov_b32_e32 v83, v82
	s_nop 1
	v_permlane32_swap_b32_e32 v82, v83
	v_add_f32_e32 v82, v82, v83
	v_fmamk_f32 v82, v82, 0x3b000000, v73
	v_mul_f32_e32 v83, 0x4b800000, v82
	v_cmp_gt_f32_e32 vcc, s31, v82
	s_nop 1
	v_cndmask_b32_e32 v82, v82, v83, vcc
	v_rsq_f32_e32 v82, v82
	s_nop 0
	v_mul_f32_e32 v83, 0x45800000, v82
	v_cndmask_b32_e32 v82, v82, v83, vcc
	v_mul_f32_e32 v74, v82, v74
	v_mul_f32_e32 v75, v82, v75
	v_mul_f32_e32 v78, v82, v78
	v_mul_f32_e32 v79, v82, v79
	v_mul_f32_e32 v76, v82, v76
	v_mul_f32_e32 v80, v82, v80
	v_mul_f32_e32 v77, v82, v77
	v_mul_f32_e32 v81, v82, v81
	v_fma_f32 v74, v12, v74, v8
	v_fma_f32 v75, v13, v75, v9
	v_fma_f32 v78, v4, v78, v0
	v_fma_f32 v79, v5, v79, v1
	v_fma_f32 v76, v14, v76, v10
	v_fma_f32 v80, v6, v80, v2
	v_fma_f32 v77, v15, v77, v11
	v_fma_f32 v81, v7, v81, v3
	v_mul_f32_e32 v82, 0xbfb8aa3b, v74
	v_mul_f32_e32 v84, 0xbfb8aa3b, v75
	v_mul_f32_e32 v83, 0xbfb8aa3b, v78
	v_mul_f32_e32 v85, 0xbfb8aa3b, v79
	v_mul_f32_e32 v86, 0xbfb8aa3b, v76
	v_mul_f32_e32 v87, 0xbfb8aa3b, v80
	v_mul_f32_e32 v88, 0xbfb8aa3b, v77
	v_mul_f32_e32 v89, 0xbfb8aa3b, v81
	v_exp_f32_e32 v82, v82
	v_exp_f32_e32 v84, v84
	v_exp_f32_e32 v83, v83
	v_exp_f32_e32 v85, v85
	v_exp_f32_e32 v86, v86
	v_exp_f32_e32 v87, v87
	v_exp_f32_e32 v88, v88
	v_exp_f32_e32 v89, v89
	v_add_f32_e32 v82, 1.0, v82
	v_add_f32_e32 v84, 1.0, v84
	v_add_f32_e32 v83, 1.0, v83
	v_add_f32_e32 v85, 1.0, v85
	v_add_f32_e32 v86, 1.0, v86
	v_add_f32_e32 v87, 1.0, v87
	v_add_f32_e32 v88, 1.0, v88
	v_add_f32_e32 v89, 1.0, v89
	v_rcp_f32_e32 v82, v82
	v_rcp_f32_e32 v84, v84
	v_rcp_f32_e32 v83, v83
	v_rcp_f32_e32 v85, v85
	v_rcp_f32_e32 v86, v86
	v_rcp_f32_e32 v87, v87
	v_rcp_f32_e32 v88, v88
	v_rcp_f32_e32 v89, v89
	v_mul_f32_e32 v74, v74, v82
	v_mul_f32_e32 v75, v75, v84
	v_mul_f32_e32 v78, v78, v83
	v_mul_f32_e32 v79, v79, v85
	v_mul_f32_e32 v76, v76, v86
	v_mul_f32_e32 v80, v80, v87
	v_mul_f32_e32 v77, v77, v88
	v_mul_f32_e32 v81, v81, v89
	v_cvt_pk_bf16_f32 v74, v74, v75
	v_cvt_pk_bf16_f32 v75, v76, v77
	global_store_dwordx2 v[28:29], v[74:75], off
	v_cvt_pk_bf16_f32 v82, v78, v79
	v_cvt_pk_bf16_f32 v83, v80, v81
	ds_read_b128 v[74:77], v72
	ds_read_b128 v[78:81], v72 offset:1024
	global_store_dwordx2 v[28:29], v[82:83], off offset:512
	s_waitcnt lgkmcnt(1)
	v_mov_b32_e32 v28, v75
	v_mov_b32_e32 v29, v76
	v_mov_b32_e32 v82, v74
	v_mov_b32_e32 v83, v77
	s_waitcnt lgkmcnt(0)
	v_mov_b32_e32 v84, v80
	v_mov_b32_e32 v85, v78
	v_mov_b32_e32 v86, v81
	v_mov_b32_e32 v87, v79
	v_pk_add_f32 v[28:29], v[28:29], v[82:83]
	v_pk_add_f32 v[82:83], v[84:85], v[86:87]
	v_add_f32_e32 v28, v28, v29
	v_add_f32_e32 v28, v28, v83
	v_add_f32_e32 v28, v82, v28
	s_waitcnt lgkmcnt(0)
	s_nop 1
	v_add_f32_dpp v28, v28, v28 quad_perm:[1,0,3,2] row_mask:0xf bank_mask:0xf
	s_nop 1
	v_add_f32_dpp v28, v28, v28 quad_perm:[2,3,0,1] row_mask:0xf bank_mask:0xf
	s_nop 1
	v_add_f32_dpp v28, v28, v28 row_half_mirror row_mask:0xf bank_mask:0xf
	s_nop 1
	v_add_f32_dpp v28, v28, v28 row_mirror row_mask:0xf bank_mask:0xf
	v_mov_b32_e32 v29, v28
	s_nop 1
	v_permlane16_swap_b32_e32 v28, v29
	v_add_f32_e32 v28, v28, v29
	v_mov_b32_e32 v29, v28
	s_nop 1
	v_permlane32_swap_b32_e32 v28, v29
	v_add_f32_e32 v28, v28, v29
	v_mul_f32_e32 v28, 0x3b000000, v28
	v_pk_add_f32 v[78:79], v[78:79], v[28:29] op_sel_hi:[1,0] neg_lo:[0,1] neg_hi:[0,1]
	v_pk_add_f32 v[74:75], v[74:75], v[28:29] op_sel_hi:[1,0] neg_lo:[0,1] neg_hi:[0,1]
	v_pk_add_f32 v[76:77], v[76:77], v[28:29] op_sel_hi:[1,0] neg_lo:[0,1] neg_hi:[0,1]
	v_pk_add_f32 v[28:29], v[80:81], v[28:29] op_sel_hi:[1,0] neg_lo:[0,1] neg_hi:[0,1]
	v_pk_mul_f32 v[80:81], v[78:79], v[78:79]
	v_pk_mul_f32 v[82:83], v[28:29], v[28:29]
	v_pk_fma_f32 v[80:81], v[74:75], v[74:75], v[80:81]
	v_pk_fma_f32 v[82:83], v[76:77], v[76:77], v[82:83]
	v_add_f32_e32 v80, v80, v81
	v_add_f32_e32 v80, v80, v82
	v_add_f32_e32 v80, v80, v83
	s_waitcnt lgkmcnt(0)
	s_nop 1
	v_add_f32_dpp v80, v80, v80 quad_perm:[1,0,3,2] row_mask:0xf bank_mask:0xf
	s_nop 1
	v_add_f32_dpp v80, v80, v80 quad_perm:[2,3,0,1] row_mask:0xf bank_mask:0xf
	s_nop 1
	v_add_f32_dpp v80, v80, v80 row_half_mirror row_mask:0xf bank_mask:0xf
	s_nop 1
	v_add_f32_dpp v80, v80, v80 row_mirror row_mask:0xf bank_mask:0xf
	v_mov_b32_e32 v81, v80
	s_nop 1
	v_permlane16_swap_b32_e32 v80, v81
	v_add_f32_e32 v80, v80, v81
	v_mov_b32_e32 v81, v80
	s_nop 1
	v_permlane32_swap_b32_e32 v80, v81
	v_add_f32_e32 v80, v80, v81
	v_fmamk_f32 v80, v80, 0x3b000000, v73
	v_mul_f32_e32 v81, 0x4b800000, v80
	v_cmp_gt_f32_e32 vcc, s31, v80
	s_nop 1
	v_cndmask_b32_e32 v80, v80, v81, vcc
	v_rsq_f32_e32 v80, v80
	s_nop 0
	v_mul_f32_e32 v81, 0x45800000, v80
	v_cndmask_b32_e32 v80, v80, v81, vcc
	v_mul_f32_e32 v74, v80, v74
	v_mul_f32_e32 v78, v80, v78
	v_mul_f32_e32 v75, v80, v75
	v_mul_f32_e32 v76, v80, v76
	v_mul_f32_e32 v28, v80, v28
	v_mul_f32_e32 v77, v80, v77
	v_mul_f32_e32 v29, v80, v29
	v_mul_f32_e32 v79, v80, v79
	v_fma_f32 v74, v12, v74, v8
	v_fma_f32 v78, v4, v78, v0
	v_fma_f32 v75, v13, v75, v9
	v_fma_f32 v76, v14, v76, v10
	v_fma_f32 v28, v6, v28, v2
	v_fma_f32 v77, v15, v77, v11
	v_fma_f32 v29, v7, v29, v3
	v_fma_f32 v79, v5, v79, v1
	v_mul_f32_e32 v80, 0xbfb8aa3b, v74
	v_mul_f32_e32 v81, 0xbfb8aa3b, v78
	v_mul_f32_e32 v82, 0xbfb8aa3b, v75
	v_mul_f32_e32 v84, 0xbfb8aa3b, v76
	v_mul_f32_e32 v85, 0xbfb8aa3b, v28
	v_mul_f32_e32 v86, 0xbfb8aa3b, v77
	v_mul_f32_e32 v87, 0xbfb8aa3b, v29
	v_mul_f32_e32 v83, 0xbfb8aa3b, v79
	v_exp_f32_e32 v80, v80
	v_exp_f32_e32 v81, v81
	v_exp_f32_e32 v82, v82
	v_exp_f32_e32 v84, v84
	v_exp_f32_e32 v85, v85
	v_exp_f32_e32 v86, v86
	v_exp_f32_e32 v87, v87
	v_exp_f32_e32 v83, v83
	v_add_f32_e32 v80, 1.0, v80
	v_add_f32_e32 v81, 1.0, v81
	v_add_f32_e32 v82, 1.0, v82
	v_add_f32_e32 v84, 1.0, v84
	v_add_f32_e32 v85, 1.0, v85
	v_add_f32_e32 v86, 1.0, v86
	v_add_f32_e32 v87, 1.0, v87
	v_add_f32_e32 v83, 1.0, v83
	v_rcp_f32_e32 v80, v80
	v_rcp_f32_e32 v81, v81
	v_rcp_f32_e32 v82, v82
	v_rcp_f32_e32 v84, v84
	v_rcp_f32_e32 v85, v85
	v_rcp_f32_e32 v86, v86
	v_rcp_f32_e32 v87, v87
	v_rcp_f32_e32 v83, v83
	v_mul_f32_e32 v74, v74, v80
	v_mul_f32_e32 v78, v78, v81
	v_mul_f32_e32 v75, v75, v82
	v_mul_f32_e32 v76, v76, v84
	v_mul_f32_e32 v80, v28, v85
	v_mul_f32_e32 v77, v77, v86
	v_mul_f32_e32 v81, v29, v87
	v_cvt_pk_bf16_f32 v28, v74, v75
	v_cvt_pk_bf16_f32 v29, v76, v77
	v_mul_f32_e32 v79, v79, v83
	global_store_dwordx2 v[26:27], v[28:29], off
	v_cvt_pk_bf16_f32 v28, v78, v79
	v_cvt_pk_bf16_f32 v29, v80, v81
	global_store_dwordx2 v[26:27], v[28:29], off offset:512
	s_barrier
	s_cbranch_scc0 .LBB0_544
